# mix epilogue pipelined (4 rows in flight), attention epilogue gain loads prefetched, redundant fences trimmed in grid barriers
# speedup vs baseline: 1.0174x; 1.0174x over previous
; DI int otid() { int t = threadIdx.x; asm volatile("" : "+v"(t)); return t; }
; DI void gbar(unsigned* ctl, unsigned& k) {
;   __syncthreads();
;   ++k;
;   if (otid() == 0) {
;     __threadfence();
;     const unsigned x = blockIdx.x & 7;
;     const unsigned gsz = (gridDim.x + 7 - x) >> 3;
;     const unsigned ngroups = gridDim.x < 8 ? gridDim.x : 8;
;     unsigned* gc = ctl + 64 + x * 32;
;     unsigned* gl = ctl + 32;
;     const unsigned old = __hip_atomic_fetch_add(gc, 1u, __ATOMIC_RELAXED, __HIP_MEMORY_SCOPE_AGENT);
;     if (old + 1 == k * gsz) {
;       __threadfence();
;       __hip_atomic_fetch_add(gl, 1u, __ATOMIC_RELAXED, __HIP_MEMORY_SCOPE_AGENT);
;     }
.LBB0_198:
	s_or_b64 exec, exec, s[6:7]
	s_xor_b32 s4, s10, 7
	s_add_i32 s4, s87, s4
	s_lshr_b32 s11, s4, 3
	s_waitcnt vmcnt(0)
	v_readfirstlane_b32 s6, v1
	s_add_u32 s4, s82, 0x42e2080
	s_addc_u32 s5, s83, 0
	v_add3_u32 v0, s6, v0, 1
	v_cmp_eq_u32_e32 vcc, s11, v0
	s_and_saveexec_b64 s[6:7], vcc
	s_cbranch_execz .LBB0_201
	s_mov_b64 s[8:9], exec
	v_mbcnt_lo_u32_b32 v0, s8, 0
	v_mbcnt_hi_u32_b32 v0, s9, v0
	v_cmp_eq_u32_e32 vcc, 0, v0
	s_and_b64 s[12:13], exec, vcc
	s_mov_b64 exec, s[12:13]
	s_cbranch_execz .LBB0_201
	s_bcnt1_i32_b64 s8, s[8:9]
	v_mov_b32_e32 v0, 0
	v_mov_b32_e32 v1, s8
	global_atomic_add v0, v1, s[4:5]

; DI void gbar(unsigned* ctl, unsigned& k) {
;     ...
;     while (__hip_atomic_load(gl, __ATOMIC_RELAXED, __HIP_MEMORY_SCOPE_AGENT) < k * ngroups) __builtin_amdgcn_s_sleep(1);
;     __threadfence();
;   }
;   __syncthreads();
; __global__ void __launch_bounds__(NTHR) fwd_megakernel(Params p) {
;     ...
;   gbar(bar, epoch);
; #pragma unroll 1
;   for (int l = 0; l < 2; ++l) {
;     if (PH & 4) phase_in_gate(p, l, smem);
;     gbar(bar, epoch);
;     if (PH & 8) phase_mixers(p, l, smem);
.LBB0_203:
	v_mov_b32_e32 v2, s10
	v_mov_b32_e32 v213, s11
	v_mov_b32_e32 v214, s6
	v_mov_b64_e32 v[0:1], s[2:3]
	buffer_inv sc1
.LBB0_204:
	s_or_b64 exec, exec, s[0:1]
	s_add_u32 s0, s82, 0x42e2000
	v_writelane_b32 v252, s0, 54
	s_addc_u32 s0, s83, 0
	v_writelane_b32 v252, s0, 55
	s_add_u32 s0, s82, 0xe00000
	v_writelane_b32 v252, s0, 56
	s_addc_u32 s0, s83, 0
	v_writelane_b32 v252, s0, 57
	s_lshr_b32 s0, s87, 3
	v_readlane_b32 s2, v252, 48
	v_mul_lo_u32 v2, s0, v2
	s_lshr_b32 s0, s2, 3
	v_add_u32_e32 v215, s0, v2
	s_add_u32 s0, s82, 0x2a643800
	s_addc_u32 s1, s83, 0
	v_writelane_b32 v252, s0, 58
	v_lshl_add_u64 v[0:1], v[0:1], 2, s[82:83]
	s_mov_b64 s[12:13], s[76:77]
	v_writelane_b32 v252, s1, 59
	s_add_u32 s0, s80, 0x317e8500
	s_addc_u32 s1, s81, 0
	v_writelane_b32 v252, s0, 60
	s_mov_b64 s[18:19], s[82:83]
	s_mov_b64 s[14:15], s[78:79]
	v_writelane_b32 v252, s1, 61
	s_add_u32 s0, s82, 0xe5c3800
	s_addc_u32 s1, s83, 0
	v_writelane_b32 v252, s0, 62
	s_mov_b64 s[16:17], s[80:81]
	s_mov_b64 s[26:27], s[18:19]
	v_writelane_b32 v252, s1, 63
	s_add_u32 s0, s82, 0x6483800
	s_addc_u32 s1, s83, 0
	v_writelane_b32 v253, s0, 0
	s_mov_b64 s[24:25], s[16:17]
	s_mov_b64 s[22:23], s[14:15]
	v_writelane_b32 v253, s1, 1
	s_add_u32 s0, s82, 0x6503800
	s_addc_u32 s1, s83, 0
	v_writelane_b32 v253, s0, 2
	s_mov_b64 s[20:21], s[12:13]
	s_mov_b64 s[12:13], s[68:69]
	v_writelane_b32 v253, s1, 3
	s_add_u32 s0, s82, 0x1a603800
	s_addc_u32 s1, s83, 0
	v_writelane_b32 v253, s0, 4
	s_mov_b64 s[14:15], s[70:71]
	v_mov_b32_e32 v179, 0
	v_writelane_b32 v253, s1, 5
	s_add_u32 s0, s82, 0x16603800
	s_addc_u32 s1, s83, 0
	v_writelane_b32 v253, s0, 6
	v_mov_b32_e32 v217, 0x3727c5ac
	v_mov_b32_e32 v218, 0x3ecc95a3
	v_writelane_b32 v253, s1, 7
	s_add_u32 s0, s82, 0x22603800
	s_addc_u32 s1, s83, 0
	v_writelane_b32 v253, s0, 8
	v_mov_b32_e32 v221, 1
	v_mov_b32_e32 v220, 0xfffffc00
	v_writelane_b32 v253, s1, 9
	s_mov_b64 s[0:1], 0x42e2100
	v_lshl_add_u64 v[176:177], v[0:1], 0, s[0:1]
	s_add_u32 s0, s82, 0x42e2080
	s_addc_u32 s1, s83, 0
	v_writelane_b32 v253, s0, 10
	v_mov_b32_e32 v222, 0xfffffe00
	v_mov_b32_e32 v223, 0xc040000
	v_writelane_b32 v253, s1, 11
	s_add_u32 s0, s82, 0x4363800
	v_writelane_b32 v253, s0, 12
	s_addc_u32 s0, s83, 0
	v_writelane_b32 v253, s0, 13
	s_add_u32 s0, s82, 0x12603800
	v_writelane_b32 v253, s0, 14
	s_addc_u32 s0, s83, 0
	v_writelane_b32 v253, s0, 15
	s_add_u32 s0, s82, 0x26603800
	s_addc_u32 s1, s83, 0
	v_writelane_b32 v253, s0, 16
	v_mov_b32_e32 v224, 0x4040000
	v_mov_b32_e32 v225, 0xc080000
	v_writelane_b32 v253, s1, 17
	s_add_u32 s0, s82, 0xa583800
	s_addc_u32 s1, s83, 0
	v_writelane_b32 v253, s0, 18
	s_cmpk_lt_i32 s2, 0x100
	v_mov_b32_e32 v210, 0x8040000
	v_writelane_b32 v253, s1, 19
	s_cselect_b64 s[0:1], -1, 0
	v_writelane_b32 v253, s0, 20
	v_mov_b32_e32 v219, 0x60
	v_mov_b32_e32 v227, 0x7f800000
	v_writelane_b32 v253, s1, 21
	s_add_u32 s0, s82, 0x1600000
	v_writelane_b32 v253, s0, 22
	s_addc_u32 s0, s83, 0
	v_writelane_b32 v253, s0, 23
	s_add_u32 s0, s82, 0x1800000
	v_writelane_b32 v253, s0, 24
	s_addc_u32 s0, s83, 0
	v_writelane_b32 v253, s0, 25
	s_add_u32 s0, s82, 0x1a00000
	v_writelane_b32 v253, s0, 26
	s_addc_u32 s0, s83, 0
	s_add_u32 s80, s18, 0x42e3000
	s_addc_u32 s81, s19, 0
	v_writelane_b32 v253, s0, 27
	s_add_u32 s0, s18, 0x3f02000
	s_addc_u32 s1, s19, 0
	v_writelane_b32 v253, s0, 28
	s_mov_b32 s83, 0
	v_mov_b32_e32 v228, 0xff800000
	v_writelane_b32 v253, s1, 29
	s_lshl_b32 s0, s87, 3
	v_writelane_b32 v253, s0, 30
	s_add_u32 s0, s18, 0x3f03000
	s_addc_u32 s1, s19, 0
	v_writelane_b32 v253, s0, 31
	v_mov_b32_e32 v229, 0x200
	v_mov_b32_e32 v230, 0x3db504f3
	v_writelane_b32 v253, s1, 32
	s_add_i32 s0, s2, 0x10000
	s_cmp_gt_i32 s0, 0x100ff
	s_cselect_b64 s[0:1], -1, 0
	s_add_u32 s3, s18, 0x1e00000
	v_writelane_b32 v253, s3, 33
	s_addc_u32 s3, s19, 0
	v_writelane_b32 v253, s3, 34
	s_add_u32 s3, s18, 0x3400000
	v_writelane_b32 v253, s3, 35
	s_addc_u32 s3, s19, 0
	s_add_u32 s8, s18, 0x3f05000
	v_writelane_b32 v253, s3, 36
	s_addc_u32 s9, s19, 0
	v_writelane_b32 v253, s8, 37
	s_lshl_b32 s3, s2, 5
	v_mov_b32_e32 v180, 0x3f317218
	v_writelane_b32 v253, s9, 38
	v_writelane_b32 v253, s3, 39
	s_lshl_b32 s3, s87, 5
	s_add_u32 s8, s18, 0x1a00040
	v_writelane_b32 v253, s3, 40
	s_addc_u32 s9, s19, 0
	v_writelane_b32 v253, s8, 41
	v_mov_b32_e32 v231, 0x7fc00000
	s_mov_b32 s33, 0x10000
	v_writelane_b32 v253, s9, 42
	s_add_u32 s8, s18, 0xe5c3840
	v_writelane_b32 v253, s12, 43
	s_addc_u32 s9, s19, 0
	s_xor_b64 s[0:1], s[0:1], -1
	v_writelane_b32 v253, s13, 44
	v_writelane_b32 v253, s14, 45
	v_writelane_b32 v253, s15, 46
	v_writelane_b32 v253, s16, 47
	v_writelane_b32 v253, s17, 48
	v_writelane_b32 v253, s18, 49
	v_writelane_b32 v253, s19, 50
	v_writelane_b32 v253, s20, 51
	v_writelane_b32 v253, s21, 52
	v_writelane_b32 v253, s22, 53
	v_writelane_b32 v253, s23, 54
	v_writelane_b32 v253, s24, 55
	v_writelane_b32 v253, s25, 56
	v_writelane_b32 v253, s26, 57
	v_writelane_b32 v253, s27, 58
	v_writelane_b32 v253, s8, 59
	s_movk_i32 s85, 0x420
	s_movk_i32 s86, 0x6000
	v_writelane_b32 v253, s9, 60
	v_writelane_b32 v253, s0, 61
	s_mov_b32 s84, 0x3fb504f3
	s_nop 0
	v_writelane_b32 v253, s1, 62
	s_lshl_b32 s0, s2, 8
	v_writelane_b32 v253, s0, 63
	s_lshl_b32 s0, s87, 8
	v_writelane_b32 v254, s0, 0
	s_mov_b32 s0, 1
	v_writelane_b32 v254, s0, 1
	s_add_i32 s0, 0, 0x12040
	v_writelane_b32 v254, s0, 2
	s_add_i32 s0, 0, 0x11840
	v_writelane_b32 v254, s0, 3
	s_add_i32 s0, 0, 0x22640
	v_writelane_b32 v254, s0, 4
	s_add_i32 s0, 0, 0x22540
	v_writelane_b32 v254, s0, 5
	s_add_i32 s0, 0, 0x22740
	v_writelane_b32 v254, s0, 6
	s_add_i32 s0, 0, 0x22440
	v_writelane_b32 v254, s0, 7
	s_add_i32 s0, 0, 0x22940
	v_writelane_b32 v254, s0, 8
	s_add_i32 s0, 0, 0x22840
	v_writelane_b32 v254, s0, 9
	s_add_i32 s0, 0, 0x1a040
	v_writelane_b32 v254, s0, 10
	s_add_i32 s0, 0, 0x22c44
	v_writelane_b32 v254, s0, 11
	s_mov_b64 s[0:1], -1
	v_writelane_b32 v254, s0, 12
	s_barrier
	s_nop 0
	v_writelane_b32 v254, s1, 13
	s_mov_b32 s0, s83
	v_writelane_b32 v254, s0, 14
	s_nop 1
	v_writelane_b32 v254, s1, 15
	v_writelane_b32 v254, s87, 16
	s_branch .LBB0_208
.LBB0_205:
	buffer_inv sc1
.LBB0_206:
	s_or_b64 exec, exec, s[0:1]
	s_barrier

; DI int otid() { int t = threadIdx.x; asm volatile("" : "+v"(t)); return t; }
; DI void gbar(unsigned* ctl, unsigned& k) {
;   __syncthreads();
;   ++k;
;   if (otid() == 0) {
;     __threadfence();
;     const unsigned x = blockIdx.x & 7;
;     const unsigned gsz = (gridDim.x + 7 - x) >> 3;
;     const unsigned ngroups = gridDim.x < 8 ? gridDim.x : 8;
;     unsigned* gc = ctl + 64 + x * 32;
;     unsigned* gl = ctl + 32;
;     const unsigned old = __hip_atomic_fetch_add(gc, 1u, __ATOMIC_RELAXED, __HIP_MEMORY_SCOPE_AGENT);
;     if (old + 1 == k * gsz) {
;       __threadfence();
;       __hip_atomic_fetch_add(gl, 1u, __ATOMIC_RELAXED, __HIP_MEMORY_SCOPE_AGENT);
;     }
.LBB0_430:
	s_or_b64 exec, exec, s[22:23]
	v_readlane_b32 s0, v254, 12
	v_readlane_b32 s1, v254, 13
	v_mov_b32_e32 v0, v212
	s_xor_b64 s[88:89], s[0:1], -1
	s_waitcnt vmcnt(0)
	s_barrier
	s_nop 0
	v_cmp_eq_u32_e32 vcc, 0, v0
	s_and_saveexec_b64 s[0:1], vcc
	s_cbranch_execz .LBB0_438
	buffer_wbl2 sc1
	buffer_inv sc1
	global_atomic_add v0, v[176:177], v221, off sc0
	v_readlane_b32 s2, v254, 1
	s_add_i32 s6, s2, 1
	v_mul_lo_u32 v1, s6, v213
	s_waitcnt vmcnt(0)
	v_add_u32_e32 v0, 1, v0
	v_cmp_eq_u32_e32 vcc, v0, v1
	s_and_saveexec_b64 s[2:3], vcc
	s_cbranch_execz .LBB0_434
	s_mov_b64 s[4:5], exec
	v_mbcnt_lo_u32_b32 v0, s4, 0
	v_mbcnt_hi_u32_b32 v0, s5, v0
	v_cmp_eq_u32_e32 vcc, 0, v0
	s_and_b64 s[8:9], exec, vcc
	s_mov_b64 exec, s[8:9]
	s_cbranch_execz .LBB0_434
	s_bcnt1_i32_b64 s4, s[4:5]
	v_mov_b32_e32 v0, s4
	v_readlane_b32 s4, v253, 10
	v_readlane_b32 s5, v253, 11
	s_nop 4
	global_atomic_add v179, v0, s[4:5]

; DI int otid() { int t = threadIdx.x; asm volatile("" : "+v"(t)); return t; }
; DI float wave_sum(float v, int lane) {
;   (void)lane;
;   int x = __float_as_int(v);
;   v += __int_as_float(__builtin_amdgcn_update_dpp(0, x, 0xB1, 0xF, 0xF, true));
;   x = __float_as_int(v);
;   v += __int_as_float(__builtin_amdgcn_update_dpp(0, x, 0x4E, 0xF, 0xF, true));
;   x = __float_as_int(v);
;   v += __int_as_float(__builtin_amdgcn_update_dpp(0, x, 0x141, 0xF, 0xF, true));
;   x = __float_as_int(v);
;   v += __int_as_float(__builtin_amdgcn_update_dpp(0, x, 0x140, 0xF, 0xF, true));
;   x = __float_as_int(v);
;   const float r0 = __int_as_float(__builtin_amdgcn_readlane(x, 0)), r1 = __int_as_float(__builtin_amdgcn_readlane(x, 16));
;   const float r2 = __int_as_float(__builtin_amdgcn_readlane(x, 32)), r3 = __int_as_float(__builtin_amdgcn_readlane(x, 48));
;   return (r0 + r1) + (r2 + r3);
; }
; DI void phase_mixers(const Params& p, int l, unsigned char* smem) {
;   const int tid0 = otid();
;   const int lane = tid0 & 63;
;   const float* lp = p.in[16] + l * 256;
;   float s1 = lp[lane] * lp[64 + lane], s2 = lp[128 + lane] * lp[192 + lane];
;   s1 = wave_sum(s1, lane); s2 = wave_sum(s2, lane);
;   const float lam_init = 0.8f - 0.6f * expf(-0.3f * (float)l);
;   const float lam = expf(s1) - expf(s2) + lam_init;
;   int* ctr = (int*)(p.ws + WS_CTR) + l;
.LBB0_436:
	s_sleep 1
	global_load_dword v1, v179, s[4:5] sc1
	s_waitcnt vmcnt(0)
	v_cmp_ge_u32_e32 vcc, v1, v0
	s_or_b64 s[2:3], vcc, s[2:3]
	s_andn2_b64 exec, exec, s[2:3]
	s_cbranch_execnz .LBB0_436
.LBB0_437:
	buffer_inv sc1
.LBB0_438:
	s_or_b64 exec, exec, s[0:1]
	v_readlane_b32 s20, v254, 14
	s_lshl_b32 s82, s20, 8
	v_mov_b32_e32 v0, v212
	s_lshl_b64 s[0:1], s[82:83], 2
	v_readlane_b32 s4, v252, 32
	s_barrier
	v_readlane_b32 s5, v252, 33
	v_and_b32_e32 v1, 63, v0
	s_add_u32 s0, s4, s0
	s_addc_u32 s1, s5, s1
	v_lshlrev_b32_e32 v1, 2, v1
	global_load_dword v2, v1, s[0:1]
	global_load_dword v3, v1, s[0:1] offset:256
	global_load_dword v5, v1, s[0:1] offset:512
	s_nop 0
	global_load_dword v1, v1, s[0:1] offset:768
	v_readlane_b32 s21, v254, 15
	v_readlane_b32 s6, v252, 34
	v_readlane_b32 s7, v252, 35
	v_readlane_b32 s8, v252, 36
	v_readlane_b32 s9, v252, 37
	v_readlane_b32 s14, v252, 42
	v_readlane_b32 s15, v252, 43
	v_cmp_eq_u32_e64 s[14:15], 0, v0
	v_mov_b32_e32 v225, 0xc080000
	v_mov_b32_e32 v224, 0x4040000
	v_mov_b32_e32 v223, 0xc040000
	v_mov_b32_e32 v222, 0xfffffe00
	v_mov_b32_e32 v221, 1
	v_mov_b32_e32 v219, 0x60
	v_readlane_b32 s10, v252, 38
	v_readlane_b32 s11, v252, 39
	v_readlane_b32 s12, v252, 40
	v_readlane_b32 s13, v252, 41
	v_readlane_b32 s16, v252, 44
	v_readlane_b32 s17, v252, 45
	v_readlane_b32 s18, v252, 46
	v_readlane_b32 s19, v252, 47
	s_waitcnt vmcnt(2)
	v_mul_f32_e32 v4, v2, v3
	s_nop 1
	v_mov_b32_dpp v4, v4 quad_perm:[1,0,3,2] row_mask:0xf bank_mask:0xf bound_ctrl:1
	v_fmac_f32_e32 v4, v2, v3
	s_waitcnt vmcnt(0)
	v_mul_f32_e32 v6, v5, v1
	v_add_f32_dpp v2, v4, v4 quad_perm:[2,3,0,1] row_mask:0xf bank_mask:0xf bound_ctrl:1
	s_nop 1
	v_add_f32_dpp v2, v2, v2 row_half_mirror row_mask:0xf bank_mask:0xf bound_ctrl:1
	s_nop 1
	v_add_f32_dpp v2, v2, v2 row_mirror row_mask:0xf bank_mask:0xf bound_ctrl:1
	s_nop 0
	v_readlane_b32 s1, v2, 16
	v_readlane_b32 s3, v2, 48
	v_readlane_b32 s0, v2, 0
	v_readlane_b32 s2, v2, 32
	v_mov_b32_e32 v2, s1
	v_mov_b32_e32 v3, s3
	v_add_f32_e32 v2, s0, v2
	v_add_f32_e32 v3, s2, v3
	v_add_f32_e32 v2, v2, v3
	s_nop 0
	v_mov_b32_dpp v3, v6 quad_perm:[1,0,3,2] row_mask:0xf bank_mask:0xf bound_ctrl:1
	v_fmac_f32_e32 v3, v5, v1
	s_nop 1
	v_add_f32_dpp v1, v3, v3 quad_perm:[2,3,0,1] row_mask:0xf bank_mask:0xf bound_ctrl:1
	s_nop 1
	v_add_f32_dpp v1, v1, v1 row_half_mirror row_mask:0xf bank_mask:0xf bound_ctrl:1
	s_nop 1
	v_add_f32_dpp v1, v1, v1 row_mirror row_mask:0xf bank_mask:0xf bound_ctrl:1
	s_nop 0
	v_readlane_b32 s1, v1, 16
	v_readlane_b32 s3, v1, 48
	v_readlane_b32 s0, v1, 0
	v_readlane_b32 s2, v1, 32
	v_mov_b32_e32 v1, s1
	v_mov_b32_e32 v3, s3
	v_add_f32_e32 v1, s0, v1
	v_add_f32_e32 v3, s2, v3
	v_add_f32_e32 v1, v1, v3
	v_cvt_f32_u32_e32 v3, s20
	s_mov_b32 s0, 0x3fb8aa3b
	s_mov_b32 s1, 0xc2ce8ed0
	s_mov_b32 s2, 0x42b17218
	v_mul_f32_e32 v3, 0xbe99999a, v3
	v_mul_f32_e32 v4, 0x3fb8aa3b, v3
	v_fma_f32 v5, v3, s0, -v4
	v_rndne_f32_e32 v6, v4
	v_fmac_f32_e32 v5, 0x32a5705f, v3
	v_sub_f32_e32 v4, v4, v6
	v_add_f32_e32 v4, v4, v5
	v_exp_f32_e32 v4, v4
	v_cvt_i32_f32_e32 v5, v6
	v_cmp_ngt_f32_e32 vcc, s1, v3
	v_ldexp_f32 v4, v4, v5
	s_nop 0
	v_cndmask_b32_e32 v4, 0, v4, vcc
	v_cmp_nlt_f32_e32 vcc, s2, v3
	s_nop 1
	v_cndmask_b32_e32 v3, v227, v4, vcc
	v_mov_b32_e32 v4, 0x3f4ccccd
	v_fmamk_f32 v3, v3, 0xbf19999a, v4
	v_mul_f32_e32 v4, 0x3fb8aa3b, v2
	v_fma_f32 v5, v2, s0, -v4
	v_rndne_f32_e32 v6, v4
	v_fmac_f32_e32 v5, 0x32a5705f, v2
	v_sub_f32_e32 v4, v4, v6
	v_add_f32_e32 v4, v4, v5
	v_exp_f32_e32 v4, v4
	v_cvt_i32_f32_e32 v5, v6
	v_cmp_ngt_f32_e32 vcc, s1, v2
	v_sub_f32_e32 v233, 1.0, v3
	v_ldexp_f32 v4, v4, v5
	v_cndmask_b32_e32 v4, 0, v4, vcc
	v_cmp_nlt_f32_e32 vcc, s2, v2
	s_nop 1
	v_cndmask_b32_e32 v2, v227, v4, vcc
	v_mul_f32_e32 v4, 0x3fb8aa3b, v1
	v_fma_f32 v5, v1, s0, -v4
	v_rndne_f32_e32 v6, v4
	v_fmac_f32_e32 v5, 0x32a5705f, v1
	v_sub_f32_e32 v4, v4, v6
	v_add_f32_e32 v4, v4, v5
	v_exp_f32_e32 v4, v4
	v_cvt_i32_f32_e32 v5, v6
	v_cmp_ngt_f32_e32 vcc, s1, v1
	s_lshl_b64 s[0:1], s[20:21], 2
	v_ldexp_f32 v4, v4, v5
	v_cndmask_b32_e32 v4, 0, v4, vcc
	v_cmp_nlt_f32_e32 vcc, s2, v1
	v_readlane_b32 s2, v252, 54
	s_add_u32 s2, s2, s0
	v_readlane_b32 s0, v252, 55
	s_addc_u32 s3, s0, s1
	v_writelane_b32 v254, s2, 17
	s_lshl_b32 s0, s20, 3
	s_lshl_b32 s82, s20, 9
	v_writelane_b32 v254, s3, 18
	v_writelane_b32 v254, s0, 19
	s_lshl_b32 s0, s20, 12
	v_writelane_b32 v254, s0, 20
	s_lshl_b32 s0, s20, 10
	v_writelane_b32 v254, s0, 21
	v_cndmask_b32_e32 v1, v227, v4, vcc
	v_sub_f32_e32 v1, v2, v1
	v_writelane_b32 v254, s1, 22
	s_lshl_b32 s0, s20, 5
	v_writelane_b32 v254, s0, 23
	s_lshl_b64 s[0:1], s[82:83], 2
	s_add_u32 s2, s6, s0
	v_writelane_b32 v254, s2, 24
	s_addc_u32 s2, s7, s1
	s_add_u32 s0, s8, s0
	v_writelane_b32 v254, s2, 25
	s_addc_u32 s1, s9, s1
	v_writelane_b32 v254, s0, 26
	v_add_f32_e32 v232, v3, v1
	s_nop 0
	v_writelane_b32 v254, s1, 27
	v_writelane_b32 v254, s14, 28
	s_nop 1
	v_writelane_b32 v254, s15, 29
	s_branch .LBB0_442

; DI float shx(float v, int mask, int lane) { return __int_as_float(__builtin_amdgcn_ds_bpermute(((lane ^ mask) & 63) << 2, __float_as_int(v))); }
; DI void attn_item(const Params& p, int l, int b, int head, int qt, float lam, float lam_init, unsigned char* smem) {
;     ...
;   if (active && comp == 0) {
;     float ss = 0.f;
; #pragma unroll
;     for (int dt = 0; dt < 4; ++dt)
; #pragma unroll
;       for (int i = 0; i < 16; ++i) {
;         const float o = O[dt][i] * inv - exch[(rg * 64 + dt * 16 + i) * 64 + lane];
;         O[dt][i] = o;
;         ss += o * o;
;       }
;     ss += shx(ss, 32, lane);
;     const float rs = rsqrtf(ss * (1.f / 128.f) + LN_EPS) * (1.f - lam_init);
;     u16* AN = (u16*)(p.ws + WS_AN) + (size_t)(qtok0 + rg * 32 + r) * 512 + head * 128;
;     const float* gw = p.in[17] + l * 512 + head * 128;
; #pragma unroll
;     for (int dt = 0; dt < 4; ++dt)
; #pragma unroll
;       for (int g = 0; g < 4; ++g) {
;         const int dv = dt * 32 + 8 * g + 4 * h;
;         const float4 g4 = *(const float4*)(gw + dv);
.LBB0_468:
	s_or_b64 exec, exec, s[0:1]
	v_cmp_eq_u32_e32 vcc, 0, v129
	s_and_b64 s[0:1], s[2:3], vcc
	s_waitcnt lgkmcnt(0)
	s_barrier
	s_and_saveexec_b64 s[2:3], s[0:1]
	s_xor_b64 s[0:1], exec, s[2:3]
	s_cbranch_execz .LBB0_470
	v_add_u32_e32 v66, 64, v64
	ds_read2_b32 v[78:79], v64 offset0:16 offset1:80
	ds_read2_b32 v[74:75], v64 offset0:144 offset1:208
	s_waitcnt vmcnt(3)
	ds_read2st64_b32 v[96:97], v66 offset0:4 offset1:5
	ds_read2st64_b32 v[88:89], v66 offset0:6 offset1:7
	ds_read2st64_b32 v[98:99], v66 offset0:8 offset1:9
	s_waitcnt vmcnt(1)
	ds_read2st64_b32 v[112:113], v66 offset0:10 offset1:11
	ds_read2st64_b32 v[114:115], v66 offset0:12 offset1:13
	ds_read2st64_b32 v[116:117], v66 offset0:14 offset1:15
	ds_read2st64_b32 v[118:119], v66 offset0:16 offset1:17
	s_waitcnt vmcnt(0)
	ds_read2st64_b32 v[120:121], v66 offset0:18 offset1:19
	ds_read2st64_b32 v[122:123], v66 offset0:20 offset1:21
	ds_read2st64_b32 v[124:125], v66 offset0:22 offset1:23
	ds_read2st64_b32 v[126:127], v66 offset0:24 offset1:25
	ds_read2st64_b32 v[134:135], v66 offset0:26 offset1:27
	ds_read2st64_b32 v[136:137], v66 offset0:28 offset1:29
	ds_read2st64_b32 v[138:139], v66 offset0:30 offset1:31
	ds_read2st64_b32 v[108:109], v66 offset0:32 offset1:33
	ds_read2st64_b32 v[140:141], v66 offset0:34 offset1:35
	ds_read2st64_b32 v[104:105], v66 offset0:36 offset1:37
	ds_read2st64_b32 v[110:111], v66 offset0:38 offset1:39
	ds_read2st64_b32 v[100:101], v66 offset0:40 offset1:41
	ds_read2st64_b32 v[106:107], v66 offset0:42 offset1:43
	ds_read2st64_b32 v[92:93], v66 offset0:44 offset1:45
	ds_read2st64_b32 v[102:103], v66 offset0:46 offset1:47
	ds_read2st64_b32 v[90:91], v66 offset0:48 offset1:49
	ds_read2st64_b32 v[94:95], v66 offset0:50 offset1:51
	ds_read2st64_b32 v[80:81], v66 offset0:52 offset1:53
	ds_read2st64_b32 v[86:87], v66 offset0:54 offset1:55
	ds_read2st64_b32 v[72:73], v66 offset0:56 offset1:57
	ds_read2st64_b32 v[76:77], v66 offset0:58 offset1:59
	ds_read2st64_b32 v[64:65], v66 offset0:60 offset1:61
	v_mov_b32_e32 v129, v179
	v_readlane_b32 s2, v252, 51
	v_readlane_b32 s3, v252, 52
	s_lshl_b32 s82, s8, 1
	s_waitcnt lgkmcnt(0)
	v_pk_fma_f32 v[64:65], v[12:13], v[68:69], v[64:65] op_sel_hi:[1,0,1] neg_lo:[0,0,1] neg_hi:[0,0,1]
	ds_read2st64_b32 v[12:13], v66 offset0:62 offset1:63
	v_lshlrev_b32_e32 v178, 1, v133
	v_pk_mul_f32 v[70:71], v[64:65], v[64:65]
	s_mov_b32 s4, 0x800000
	s_waitcnt lgkmcnt(0)
	v_pk_fma_f32 v[66:67], v[14:15], v[68:69], v[12:13] op_sel_hi:[1,0,1] neg_lo:[0,0,1] neg_hi:[0,0,1]
	v_lshlrev_b64 v[12:13], 10, v[128:129]
	v_lshl_add_u64 v[12:13], s[2:3], 0, v[12:13]
	s_lshl_b32 s2, s8, 2
	v_readlane_b32 s3, v254, 24
	v_lshlrev_b32_e32 v69, 2, v133
	s_add_u32 s2, s3, s2
	v_readlane_b32 s3, v254, 25
	v_pk_fma_f32 v[84:85], v[48:49], v[68:69], v[78:79] op_sel_hi:[1,0,1] neg_lo:[0,0,1] neg_hi:[0,0,1]
	s_addc_u32 s3, s3, 0
	v_pk_fma_f32 v[74:75], v[50:51], v[68:69], v[74:75] op_sel_hi:[1,0,1] neg_lo:[0,0,1] neg_hi:[0,0,1]
	v_pk_mul_f32 v[144:145], v[84:85], v[84:85]
	v_lshl_add_u64 v[128:129], v[12:13], 0, s[82:83]
	v_pk_mul_f32 v[142:143], v[74:75], v[74:75]
	global_load_dwordx4 v[12:15], v69, s[2:3]
	global_load_dwordx4 v[148:151], v69, s[2:3] offset:32
	global_load_dwordx4 v[152:155], v69, s[2:3] offset:64
	global_load_dwordx4 v[156:159], v69, s[2:3] offset:96
	global_load_dwordx4 v[160:163], v69, s[2:3] offset:128
	global_load_dwordx4 v[164:167], v69, s[2:3] offset:160
	global_load_dwordx4 v[168:171], v69, s[2:3] offset:192
	global_load_dwordx4 v[244:247], v69, s[2:3] offset:224
	global_load_dwordx4 v[248:251], v69, s[2:3] offset:256
	v_pk_fma_f32 v[88:89], v[54:55], v[68:69], v[88:89] op_sel_hi:[1,0,1] neg_lo:[0,0,1] neg_hi:[0,0,1]
	v_pk_fma_f32 v[96:97], v[52:53], v[68:69], v[96:97] op_sel_hi:[1,0,1] neg_lo:[0,0,1] neg_hi:[0,0,1]
	v_pk_fma_f32 v[78:79], v[58:59], v[68:69], v[112:113] op_sel_hi:[1,0,1] neg_lo:[0,0,1] neg_hi:[0,0,1]
	v_pk_fma_f32 v[98:99], v[56:57], v[68:69], v[98:99] op_sel_hi:[1,0,1] neg_lo:[0,0,1] neg_hi:[0,0,1]
	v_pk_fma_f32 v[62:63], v[62:63], v[68:69], v[116:117] op_sel_hi:[1,0,1] neg_lo:[0,0,1] neg_hi:[0,0,1]
	v_pk_fma_f32 v[60:61], v[60:61], v[68:69], v[114:115] op_sel_hi:[1,0,1] neg_lo:[0,0,1] neg_hi:[0,0,1]
	v_pk_fma_f32 v[56:57], v[34:35], v[68:69], v[120:121] op_sel_hi:[1,0,1] neg_lo:[0,0,1] neg_hi:[0,0,1]
	v_pk_fma_f32 v[58:59], v[32:33], v[68:69], v[118:119] op_sel_hi:[1,0,1] neg_lo:[0,0,1] neg_hi:[0,0,1]
	v_pk_fma_f32 v[50:51], v[38:39], v[68:69], v[124:125] op_sel_hi:[1,0,1] neg_lo:[0,0,1] neg_hi:[0,0,1]
	v_pk_fma_f32 v[54:55], v[36:37], v[68:69], v[122:123] op_sel_hi:[1,0,1] neg_lo:[0,0,1] neg_hi:[0,0,1]
	v_pk_fma_f32 v[42:43], v[42:43], v[68:69], v[134:135] op_sel_hi:[1,0,1] neg_lo:[0,0,1] neg_hi:[0,0,1]
	v_pk_fma_f32 v[52:53], v[40:41], v[68:69], v[126:127] op_sel_hi:[1,0,1] neg_lo:[0,0,1] neg_hi:[0,0,1]
	v_pk_fma_f32 v[40:41], v[46:47], v[68:69], v[138:139] op_sel_hi:[1,0,1] neg_lo:[0,0,1] neg_hi:[0,0,1]
	v_pk_fma_f32 v[44:45], v[44:45], v[68:69], v[136:137] op_sel_hi:[1,0,1] neg_lo:[0,0,1] neg_hi:[0,0,1]
	v_pk_fma_f32 v[36:37], v[18:19], v[68:69], v[140:141] op_sel_hi:[1,0,1] neg_lo:[0,0,1] neg_hi:[0,0,1]
	v_pk_fma_f32 v[38:39], v[16:17], v[68:69], v[108:109] op_sel_hi:[1,0,1] neg_lo:[0,0,1] neg_hi:[0,0,1]
	v_pk_fma_f32 v[32:33], v[22:23], v[68:69], v[110:111] op_sel_hi:[1,0,1] neg_lo:[0,0,1] neg_hi:[0,0,1]
	v_pk_fma_f32 v[34:35], v[20:21], v[68:69], v[104:105] op_sel_hi:[1,0,1] neg_lo:[0,0,1] neg_hi:[0,0,1]
	v_pk_fma_f32 v[22:23], v[26:27], v[68:69], v[106:107] op_sel_hi:[1,0,1] neg_lo:[0,0,1] neg_hi:[0,0,1]
	v_pk_fma_f32 v[26:27], v[24:25], v[68:69], v[100:101] op_sel_hi:[1,0,1] neg_lo:[0,0,1] neg_hi:[0,0,1]
; DI float shx(float v, int mask, int lane) { return __int_as_float(__builtin_amdgcn_ds_bpermute(((lane ^ mask) & 63) << 2, __float_as_int(v))); }
; DI void attn_item(const Params& p, int l, int b, int head, int qt, float lam, float lam_init, unsigned char* smem) {
;     ...
;     float ss = 0.f;
; #pragma unroll
;     for (int dt = 0; dt < 4; ++dt)
; #pragma unroll
;       for (int i = 0; i < 16; ++i) {
;         const float o = O[dt][i] * inv - exch[(rg * 64 + dt * 16 + i) * 64 + lane];
;         O[dt][i] = o;
;         ss += o * o;
;       }
;     ss += shx(ss, 32, lane);
;     const float rs = rsqrtf(ss * (1.f / 128.f) + LN_EPS) * (1.f - lam_init);
	v_pk_fma_f32 v[20:21], v[30:31], v[68:69], v[102:103] op_sel_hi:[1,0,1] neg_lo:[0,0,1] neg_hi:[0,0,1]
	v_pk_fma_f32 v[24:25], v[28:29], v[68:69], v[92:93] op_sel_hi:[1,0,1] neg_lo:[0,0,1] neg_hi:[0,0,1]
	v_pk_fma_f32 v[16:17], v[2:3], v[68:69], v[94:95] op_sel_hi:[1,0,1] neg_lo:[0,0,1] neg_hi:[0,0,1]
	v_pk_fma_f32 v[18:19], v[0:1], v[68:69], v[90:91] op_sel_hi:[1,0,1] neg_lo:[0,0,1] neg_hi:[0,0,1]
	v_pk_fma_f32 v[2:3], v[6:7], v[68:69], v[86:87] op_sel_hi:[1,0,1] neg_lo:[0,0,1] neg_hi:[0,0,1]
	v_pk_fma_f32 v[6:7], v[4:5], v[68:69], v[80:81] op_sel_hi:[1,0,1] neg_lo:[0,0,1] neg_hi:[0,0,1]
	v_pk_fma_f32 v[0:1], v[10:11], v[68:69], v[76:77] op_sel_hi:[1,0,1] neg_lo:[0,0,1] neg_hi:[0,0,1]
	v_pk_fma_f32 v[4:5], v[8:9], v[68:69], v[72:73] op_sel_hi:[1,0,1] neg_lo:[0,0,1] neg_hi:[0,0,1]
	v_add_f32_e32 v68, v144, v145
	v_add_f32_e32 v68, v68, v142
	v_pk_mul_f32 v[132:133], v[96:97], v[96:97]
	v_add_f32_e32 v68, v68, v143
	v_add_f32_e32 v68, v68, v132
	v_lshl_add_u64 v[48:49], v[128:129], 0, v[178:179]
	v_pk_mul_f32 v[128:129], v[88:89], v[88:89]
	v_add_f32_e32 v68, v68, v133
	v_add_f32_e32 v68, v68, v128
	v_pk_mul_f32 v[146:147], v[98:99], v[98:99]
	v_add_f32_e32 v68, v68, v129
	v_add_f32_e32 v68, v68, v146
	v_pk_mul_f32 v[112:113], v[78:79], v[78:79]
	v_add_f32_e32 v68, v68, v147
	v_add_f32_e32 v68, v68, v112
	v_pk_mul_f32 v[114:115], v[60:61], v[60:61]
	v_add_f32_e32 v68, v68, v113
	v_add_f32_e32 v68, v68, v114
	v_pk_mul_f32 v[116:117], v[62:63], v[62:63]
	v_add_f32_e32 v68, v68, v115
	v_add_f32_e32 v68, v68, v116
	v_pk_mul_f32 v[118:119], v[58:59], v[58:59]
	v_add_f32_e32 v68, v68, v117
	v_add_f32_e32 v68, v68, v118
	v_pk_mul_f32 v[120:121], v[56:57], v[56:57]
	v_add_f32_e32 v68, v68, v119
	v_add_f32_e32 v68, v68, v120
	v_pk_mul_f32 v[122:123], v[54:55], v[54:55]
	v_add_f32_e32 v68, v68, v121
	v_add_f32_e32 v68, v68, v122
	v_pk_mul_f32 v[124:125], v[50:51], v[50:51]
	v_add_f32_e32 v68, v68, v123
	v_add_f32_e32 v68, v68, v124
	v_pk_mul_f32 v[126:127], v[52:53], v[52:53]
	v_add_f32_e32 v68, v68, v125
	v_add_f32_e32 v68, v68, v126
	v_pk_mul_f32 v[134:135], v[42:43], v[42:43]
	v_add_f32_e32 v68, v68, v127
	v_add_f32_e32 v68, v68, v134
	v_pk_mul_f32 v[136:137], v[44:45], v[44:45]
	v_add_f32_e32 v68, v68, v135
	v_add_f32_e32 v68, v68, v136
	v_pk_mul_f32 v[46:47], v[40:41], v[40:41]
	v_add_f32_e32 v68, v68, v137
	v_add_f32_e32 v46, v68, v46
	v_pk_mul_f32 v[108:109], v[38:39], v[38:39]
	v_add_f32_e32 v46, v46, v47
	v_add_f32_e32 v46, v46, v108
	v_pk_mul_f32 v[138:139], v[36:37], v[36:37]
	v_add_f32_e32 v46, v46, v109
	v_add_f32_e32 v46, v46, v138
	v_pk_mul_f32 v[104:105], v[34:35], v[34:35]
	v_add_f32_e32 v46, v46, v139
	v_add_f32_e32 v46, v46, v104
	v_pk_mul_f32 v[110:111], v[32:33], v[32:33]
	v_add_f32_e32 v46, v46, v105
	v_add_f32_e32 v46, v46, v110
	v_pk_mul_f32 v[100:101], v[26:27], v[26:27]
	v_add_f32_e32 v46, v46, v111
	v_add_f32_e32 v46, v46, v100
	v_pk_mul_f32 v[106:107], v[22:23], v[22:23]
	v_add_f32_e32 v46, v46, v101
	v_add_f32_e32 v46, v46, v106
	v_pk_mul_f32 v[28:29], v[24:25], v[24:25]
	v_add_f32_e32 v46, v46, v107
	v_add_f32_e32 v28, v46, v28
	v_pk_mul_f32 v[30:31], v[20:21], v[20:21]
	v_add_f32_e32 v28, v28, v29
	v_add_f32_e32 v28, v28, v30
	v_pk_mul_f32 v[90:91], v[18:19], v[18:19]
	v_add_f32_e32 v28, v28, v31
	v_add_f32_e32 v28, v28, v90
	v_pk_mul_f32 v[92:93], v[16:17], v[16:17]
	v_add_f32_e32 v28, v28, v91
	v_add_f32_e32 v28, v28, v92
	v_pk_mul_f32 v[80:81], v[6:7], v[6:7]
	v_add_f32_e32 v28, v28, v93
	v_add_f32_e32 v28, v28, v80
	v_pk_mul_f32 v[86:87], v[2:3], v[2:3]
	v_add_f32_e32 v28, v28, v81
	v_add_f32_e32 v28, v28, v86
	v_pk_mul_f32 v[8:9], v[4:5], v[4:5]
	v_add_f32_e32 v28, v28, v87
	v_add_f32_e32 v8, v28, v8
	v_pk_mul_f32 v[10:11], v[0:1], v[0:1]
	v_add_f32_e32 v8, v8, v9
	v_add_f32_e32 v8, v8, v10
	v_add_f32_e32 v8, v8, v11
	v_add_f32_e32 v8, v8, v70
	v_pk_mul_f32 v[82:83], v[66:67], v[66:67]
	v_add_f32_e32 v8, v8, v71
	v_add_f32_e32 v8, v8, v82
	v_add_f32_e32 v8, v8, v83
	ds_bpermute_b32 v9, v131, v8
	s_waitcnt lgkmcnt(0)
	v_add_f32_e32 v8, v8, v9
	v_fmamk_f32 v8, v8, 0x3c000000, v217
	v_cmp_gt_f32_e32 vcc, s4, v8
	v_mul_f32_e32 v9, 0x4b800000, v8
	s_nop 0
	v_cndmask_b32_e32 v8, v8, v9, vcc
	v_rsq_f32_e32 v8, v8
	s_nop 0
	v_mul_f32_e32 v9, 0x45800000, v8
	v_cndmask_b32_e32 v8, v8, v9, vcc
	v_mul_f32_e32 v8, v233, v8
	v_pk_mul_f32 v[10:11], v[84:85], v[8:9] op_sel_hi:[1,0]
	v_pk_mul_f32 v[6:7], v[6:7], v[8:9] op_sel_hi:[1,0]
	s_waitcnt vmcnt(0)
; DI void attn_item(const Params& p, int l, int b, int head, int qt, float lam, float lam_init, unsigned char* smem) {
;     ...
;     u16* AN = (u16*)(p.ws + WS_AN) + (size_t)(qtok0 + rg * 32 + r) * 512 + head * 128;
;     const float* gw = p.in[17] + l * 512 + head * 128;
; #pragma unroll
;     for (int dt = 0; dt < 4; ++dt)
; #pragma unroll
;       for (int g = 0; g < 4; ++g) {
;         const int dv = dt * 32 + 8 * g + 4 * h;
;         const float4 g4 = *(const float4*)(gw + dv);
;         uint2 o;
;         o.x = pack2(O[dt][4 * g] * rs * g4.x, O[dt][4 * g + 1] * rs * g4.y);
;         o.y = pack2(O[dt][4 * g + 2] * rs * g4.z, O[dt][4 * g + 3] * rs * g4.w);
;         *(uint2*)(AN + dv) = o;
;       }
	v_pk_mul_f32 v[10:11], v[12:13], v[10:11]
	v_pk_mul_f32 v[12:13], v[74:75], v[8:9] op_sel_hi:[1,0]
	v_cvt_pk_bf16_f32 v10, v10, v11
	v_pk_mul_f32 v[12:13], v[14:15], v[12:13]
	v_pk_mul_f32 v[14:15], v[96:97], v[8:9] op_sel_hi:[1,0]
	v_cvt_pk_bf16_f32 v11, v12, v13
	global_store_dwordx2 v[48:49], v[10:11], off
	v_mov_b64_e32 v[10:11], v[148:149]
	v_mov_b64_e32 v[12:13], v[150:151]
	global_load_dwordx4 v[148:151], v69, s[2:3] offset:288
	v_pk_mul_f32 v[2:3], v[2:3], v[8:9] op_sel_hi:[1,0]
	v_pk_mul_f32 v[0:1], v[0:1], v[8:9] op_sel_hi:[1,0]
	v_pk_mul_f32 v[10:11], v[10:11], v[14:15]
	v_pk_mul_f32 v[14:15], v[88:89], v[8:9] op_sel_hi:[1,0]
	v_cvt_pk_bf16_f32 v10, v10, v11
	v_pk_mul_f32 v[12:13], v[12:13], v[14:15]
	v_pk_mul_f32 v[14:15], v[98:99], v[8:9] op_sel_hi:[1,0]
	v_cvt_pk_bf16_f32 v11, v12, v13
	global_store_dwordx2 v[48:49], v[10:11], off offset:16
	v_mov_b64_e32 v[10:11], v[152:153]
	v_mov_b64_e32 v[12:13], v[154:155]
	global_load_dwordx4 v[152:155], v69, s[2:3] offset:320
	v_pk_mul_f32 v[10:11], v[14:15], v[10:11]
	v_pk_mul_f32 v[14:15], v[78:79], v[8:9] op_sel_hi:[1,0]
	v_cvt_pk_bf16_f32 v10, v10, v11
	v_pk_mul_f32 v[12:13], v[14:15], v[12:13]
	v_pk_mul_f32 v[14:15], v[60:61], v[8:9] op_sel_hi:[1,0]
	v_cvt_pk_bf16_f32 v11, v12, v13
	global_store_dwordx2 v[48:49], v[10:11], off offset:32
	v_mov_b64_e32 v[10:11], v[156:157]
	v_mov_b64_e32 v[12:13], v[158:159]
	global_load_dwordx4 v[156:159], v69, s[2:3] offset:352
	v_pk_mul_f32 v[10:11], v[14:15], v[10:11]
	v_pk_mul_f32 v[14:15], v[62:63], v[8:9] op_sel_hi:[1,0]
	v_cvt_pk_bf16_f32 v10, v10, v11
	v_pk_mul_f32 v[12:13], v[14:15], v[12:13]
	v_pk_mul_f32 v[14:15], v[58:59], v[8:9] op_sel_hi:[1,0]
	v_cvt_pk_bf16_f32 v11, v12, v13
	global_store_dwordx2 v[48:49], v[10:11], off offset:48
	v_mov_b64_e32 v[10:11], v[160:161]
	v_mov_b64_e32 v[12:13], v[162:163]
	global_load_dwordx4 v[160:163], v69, s[2:3] offset:384
	v_pk_mul_f32 v[10:11], v[14:15], v[10:11]
	v_pk_mul_f32 v[14:15], v[56:57], v[8:9] op_sel_hi:[1,0]
	v_cvt_pk_bf16_f32 v10, v10, v11
	v_pk_mul_f32 v[12:13], v[14:15], v[12:13]
	v_pk_mul_f32 v[14:15], v[54:55], v[8:9] op_sel_hi:[1,0]
	v_cvt_pk_bf16_f32 v11, v12, v13
	global_store_dwordx2 v[48:49], v[10:11], off offset:64
	v_mov_b64_e32 v[10:11], v[164:165]
	v_mov_b64_e32 v[12:13], v[166:167]
	global_load_dwordx4 v[164:167], v69, s[2:3] offset:416
	v_pk_mul_f32 v[10:11], v[14:15], v[10:11]
	v_pk_mul_f32 v[14:15], v[50:51], v[8:9] op_sel_hi:[1,0]
	v_cvt_pk_bf16_f32 v10, v10, v11
	v_pk_mul_f32 v[12:13], v[14:15], v[12:13]
	v_pk_mul_f32 v[14:15], v[52:53], v[8:9] op_sel_hi:[1,0]
	v_cvt_pk_bf16_f32 v11, v12, v13
	global_store_dwordx2 v[48:49], v[10:11], off offset:80
	v_mov_b64_e32 v[10:11], v[168:169]
	v_mov_b64_e32 v[12:13], v[170:171]
	global_load_dwordx4 v[168:171], v69, s[2:3] offset:448
	v_pk_mul_f32 v[10:11], v[14:15], v[10:11]
	v_pk_mul_f32 v[14:15], v[42:43], v[8:9] op_sel_hi:[1,0]
	v_cvt_pk_bf16_f32 v10, v10, v11
	v_pk_mul_f32 v[12:13], v[14:15], v[12:13]
	v_pk_mul_f32 v[14:15], v[44:45], v[8:9] op_sel_hi:[1,0]
	v_cvt_pk_bf16_f32 v11, v12, v13
	global_store_dwordx2 v[48:49], v[10:11], off offset:96
	v_mov_b64_e32 v[10:11], v[244:245]
	v_mov_b64_e32 v[12:13], v[246:247]
	global_load_dwordx4 v[244:247], v69, s[2:3] offset:480
	v_pk_mul_f32 v[10:11], v[14:15], v[10:11]
	v_pk_mul_f32 v[14:15], v[40:41], v[8:9] op_sel_hi:[1,0]
	v_cvt_pk_bf16_f32 v10, v10, v11
	v_pk_mul_f32 v[12:13], v[14:15], v[12:13]
	v_pk_mul_f32 v[14:15], v[38:39], v[8:9] op_sel_hi:[1,0]
	v_cvt_pk_bf16_f32 v11, v12, v13
	global_store_dwordx2 v[48:49], v[10:11], off offset:112
	v_mov_b64_e32 v[10:11], v[248:249]
	v_mov_b64_e32 v[12:13], v[250:251]
	v_pk_mul_f32 v[10:11], v[14:15], v[10:11]
	v_pk_mul_f32 v[14:15], v[36:37], v[8:9] op_sel_hi:[1,0]
	v_cvt_pk_bf16_f32 v10, v10, v11
	v_pk_mul_f32 v[12:13], v[14:15], v[12:13]
	v_pk_mul_f32 v[14:15], v[34:35], v[8:9] op_sel_hi:[1,0]
	v_cvt_pk_bf16_f32 v11, v12, v13
	global_store_dwordx2 v[48:49], v[10:11], off offset:128
	s_waitcnt vmcnt(14)
	v_mov_b64_e32 v[10:11], v[148:149]
	v_mov_b64_e32 v[12:13], v[150:151]
	v_pk_mul_f32 v[10:11], v[14:15], v[10:11]
	v_pk_mul_f32 v[14:15], v[32:33], v[8:9] op_sel_hi:[1,0]
	v_cvt_pk_bf16_f32 v10, v10, v11
	v_pk_mul_f32 v[12:13], v[14:15], v[12:13]
	v_pk_mul_f32 v[14:15], v[26:27], v[8:9] op_sel_hi:[1,0]
	v_cvt_pk_bf16_f32 v11, v12, v13
	global_store_dwordx2 v[48:49], v[10:11], off offset:144
	s_waitcnt vmcnt(13)
	v_mov_b64_e32 v[10:11], v[152:153]
	v_mov_b64_e32 v[12:13], v[154:155]
	v_pk_mul_f32 v[10:11], v[14:15], v[10:11]
	v_pk_mul_f32 v[14:15], v[22:23], v[8:9] op_sel_hi:[1,0]
	v_cvt_pk_bf16_f32 v10, v10, v11
	v_pk_mul_f32 v[12:13], v[14:15], v[12:13]
	v_pk_mul_f32 v[14:15], v[24:25], v[8:9] op_sel_hi:[1,0]
	v_cvt_pk_bf16_f32 v11, v12, v13
	global_store_dwordx2 v[48:49], v[10:11], off offset:160
	s_waitcnt vmcnt(12)
	v_mov_b64_e32 v[10:11], v[156:157]
	v_mov_b64_e32 v[12:13], v[158:159]
	v_pk_mul_f32 v[10:11], v[14:15], v[10:11]
	v_pk_mul_f32 v[14:15], v[20:21], v[8:9] op_sel_hi:[1,0]
	v_cvt_pk_bf16_f32 v10, v10, v11
	v_pk_mul_f32 v[12:13], v[14:15], v[12:13]
	v_pk_mul_f32 v[14:15], v[18:19], v[8:9] op_sel_hi:[1,0]
	v_cvt_pk_bf16_f32 v11, v12, v13
	global_store_dwordx2 v[48:49], v[10:11], off offset:176
	s_waitcnt vmcnt(11)
	v_mov_b64_e32 v[10:11], v[160:161]
	v_mov_b64_e32 v[12:13], v[162:163]
	v_pk_mul_f32 v[10:11], v[14:15], v[10:11]
	v_pk_mul_f32 v[14:15], v[16:17], v[8:9] op_sel_hi:[1,0]
	v_cvt_pk_bf16_f32 v10, v10, v11
	v_pk_mul_f32 v[12:13], v[14:15], v[12:13]
	s_nop 0
	v_cvt_pk_bf16_f32 v11, v12, v13
	global_store_dwordx2 v[48:49], v[10:11], off offset:192
	s_waitcnt vmcnt(10)
	v_mov_b64_e32 v[10:11], v[164:165]
	v_mov_b64_e32 v[12:13], v[166:167]
	v_pk_mul_f32 v[6:7], v[6:7], v[10:11]
	v_pk_mul_f32 v[2:3], v[2:3], v[12:13]
	v_cvt_pk_bf16_f32 v6, v6, v7
	v_cvt_pk_bf16_f32 v7, v2, v3
	global_store_dwordx2 v[48:49], v[6:7], off offset:208
	s_waitcnt vmcnt(9)
	v_mov_b64_e32 v[10:11], v[168:169]
	v_mov_b64_e32 v[12:13], v[170:171]
	v_pk_mul_f32 v[2:3], v[4:5], v[8:9] op_sel_hi:[1,0]
	v_pk_mul_f32 v[4:5], v[64:65], v[8:9] op_sel_hi:[1,0]
	v_pk_mul_f32 v[2:3], v[2:3], v[10:11]
	v_pk_mul_f32 v[0:1], v[0:1], v[12:13]
	v_cvt_pk_bf16_f32 v2, v2, v3
	v_cvt_pk_bf16_f32 v3, v0, v1
	global_store_dwordx2 v[48:49], v[2:3], off offset:224
	s_waitcnt vmcnt(8)
	v_mov_b64_e32 v[0:1], v[244:245]
	v_mov_b64_e32 v[2:3], v[246:247]
	v_pk_mul_f32 v[0:1], v[4:5], v[0:1]
	v_pk_mul_f32 v[4:5], v[66:67], v[8:9] op_sel_hi:[1,0]
	v_cvt_pk_bf16_f32 v0, v0, v1
	v_pk_mul_f32 v[2:3], v[4:5], v[2:3]
	s_nop 0
	v_cvt_pk_bf16_f32 v1, v2, v3
	global_store_dwordx2 v[48:49], v[0:1], off offset:240

; DI float shx(float v, int mask, int lane) { return __int_as_float(__builtin_amdgcn_ds_bpermute(((lane ^ mask) & 63) << 2, __float_as_int(v))); }
; DI void attn_item(const Params& p, int l, int b, int head, int qt, float lam, float lam_init, unsigned char* smem) {
;     ...
;   if (active && comp == 0) {
;     float ss = 0.f;
; #pragma unroll
;     for (int dt = 0; dt < 4; ++dt)
; #pragma unroll
;       for (int i = 0; i < 16; ++i) {
;         const float o = O[dt][i] * inv - exch[(rg * 64 + dt * 16 + i) * 64 + lane];
;         O[dt][i] = o;
;         ss += o * o;
;       }
;     ss += shx(ss, 32, lane);
;     const float rs = rsqrtf(ss * (1.f / 128.f) + LN_EPS) * (1.f - lam_init);
;     u16* AN = (u16*)(p.ws + WS_AN) + (size_t)(qtok0 + rg * 32 + r) * 512 + head * 128;
;     const float* gw = p.in[17] + l * 512 + head * 128;
; #pragma unroll
;     for (int dt = 0; dt < 4; ++dt)
; #pragma unroll
;       for (int g = 0; g < 4; ++g) {
;         const int dv = dt * 32 + 8 * g + 4 * h;
;         const float4 g4 = *(const float4*)(gw + dv);
.LBB0_490:
	s_or_b64 exec, exec, s[2:3]
	s_waitcnt lgkmcnt(0)
	s_barrier
	s_and_saveexec_b64 s[0:1], vcc
	v_readlane_b32 s14, v254, 28
	s_xor_b64 s[0:1], exec, s[0:1]
	v_readlane_b32 s15, v254, 29
	s_cbranch_execz .LBB0_492
	v_add_u32_e32 v66, 64, v64
	ds_read2_b32 v[76:77], v64 offset0:16 offset1:80
	ds_read2_b32 v[74:75], v64 offset0:144 offset1:208
	ds_read2st64_b32 v[94:95], v66 offset0:4 offset1:5
	ds_read2st64_b32 v[86:87], v66 offset0:6 offset1:7
	s_waitcnt vmcnt(3)
	ds_read2st64_b32 v[96:97], v66 offset0:8 offset1:9
	s_waitcnt vmcnt(1)
	ds_read2st64_b32 v[104:105], v66 offset0:10 offset1:11
	ds_read2st64_b32 v[106:107], v66 offset0:12 offset1:13
	ds_read2st64_b32 v[108:109], v66 offset0:14 offset1:15
	ds_read2st64_b32 v[110:111], v66 offset0:16 offset1:17
	ds_read2st64_b32 v[112:113], v66 offset0:18 offset1:19
	ds_read2st64_b32 v[114:115], v66 offset0:20 offset1:21
	ds_read2st64_b32 v[116:117], v66 offset0:22 offset1:23
	ds_read2st64_b32 v[118:119], v66 offset0:24 offset1:25
	s_waitcnt vmcnt(0)
	ds_read2st64_b32 v[120:121], v66 offset0:26 offset1:27
	ds_read2st64_b32 v[122:123], v66 offset0:28 offset1:29
	ds_read2st64_b32 v[124:125], v66 offset0:30 offset1:31
	ds_read2st64_b32 v[126:127], v66 offset0:32 offset1:33
	ds_read2st64_b32 v[134:135], v66 offset0:34 offset1:35
	ds_read2st64_b32 v[136:137], v66 offset0:36 offset1:37
	ds_read2st64_b32 v[138:139], v66 offset0:38 offset1:39
	ds_read2st64_b32 v[100:101], v66 offset0:40 offset1:41
	ds_read2st64_b32 v[140:141], v66 offset0:42 offset1:43
	ds_read2st64_b32 v[92:93], v66 offset0:44 offset1:45
	ds_read2st64_b32 v[102:103], v66 offset0:46 offset1:47
	ds_read2st64_b32 v[90:91], v66 offset0:48 offset1:49
	ds_read2st64_b32 v[98:99], v66 offset0:50 offset1:51
	ds_read2st64_b32 v[80:81], v66 offset0:52 offset1:53
	ds_read2st64_b32 v[88:89], v66 offset0:54 offset1:55
	ds_read2st64_b32 v[72:73], v66 offset0:56 offset1:57
	ds_read2st64_b32 v[78:79], v66 offset0:58 offset1:59
	ds_read2st64_b32 v[64:65], v66 offset0:60 offset1:61
	v_readlane_b32 s2, v252, 51
	v_readlane_b32 s3, v252, 52
	s_lshl_b32 s82, s11, 1
	v_lshlrev_b32_e32 v178, 1, v133
	s_waitcnt lgkmcnt(0)
	v_pk_fma_f32 v[64:65], v[12:13], v[68:69], v[64:65] op_sel_hi:[1,0,1] neg_lo:[0,0,1] neg_hi:[0,0,1]
	ds_read2st64_b32 v[12:13], v66 offset0:62 offset1:63
	v_pk_mul_f32 v[70:71], v[64:65], v[64:65]
	s_mov_b32 s4, 0x800000
	s_waitcnt lgkmcnt(0)
	v_pk_fma_f32 v[66:67], v[14:15], v[68:69], v[12:13] op_sel_hi:[1,0,1] neg_lo:[0,0,1] neg_hi:[0,0,1]
	v_lshl_add_u64 v[12:13], s[2:3], 0, v[128:129]
	s_lshl_b32 s2, s11, 2
	v_readlane_b32 s3, v254, 24
	v_lshlrev_b32_e32 v69, 2, v133
	s_add_u32 s2, s3, s2
	v_readlane_b32 s3, v254, 25
	v_pk_fma_f32 v[84:85], v[48:49], v[68:69], v[76:77] op_sel_hi:[1,0,1] neg_lo:[0,0,1] neg_hi:[0,0,1]
	s_addc_u32 s3, s3, 0
	v_pk_fma_f32 v[74:75], v[50:51], v[68:69], v[74:75] op_sel_hi:[1,0,1] neg_lo:[0,0,1] neg_hi:[0,0,1]
	v_pk_mul_f32 v[144:145], v[84:85], v[84:85]
	v_lshl_add_u64 v[128:129], v[12:13], 0, s[82:83]
	v_pk_mul_f32 v[142:143], v[74:75], v[74:75]
	global_load_dwordx4 v[12:15], v69, s[2:3]
	global_load_dwordx4 v[148:151], v69, s[2:3] offset:32
	global_load_dwordx4 v[152:155], v69, s[2:3] offset:64
	global_load_dwordx4 v[156:159], v69, s[2:3] offset:96
	global_load_dwordx4 v[160:163], v69, s[2:3] offset:128
	global_load_dwordx4 v[164:167], v69, s[2:3] offset:160
	global_load_dwordx4 v[168:171], v69, s[2:3] offset:192
	global_load_dwordx4 v[244:247], v69, s[2:3] offset:224
	global_load_dwordx4 v[248:251], v69, s[2:3] offset:256
	v_pk_fma_f32 v[86:87], v[54:55], v[68:69], v[86:87] op_sel_hi:[1,0,1] neg_lo:[0,0,1] neg_hi:[0,0,1]
	v_pk_fma_f32 v[94:95], v[52:53], v[68:69], v[94:95] op_sel_hi:[1,0,1] neg_lo:[0,0,1] neg_hi:[0,0,1]
	v_pk_fma_f32 v[76:77], v[58:59], v[68:69], v[104:105] op_sel_hi:[1,0,1] neg_lo:[0,0,1] neg_hi:[0,0,1]
	v_pk_fma_f32 v[96:97], v[56:57], v[68:69], v[96:97] op_sel_hi:[1,0,1] neg_lo:[0,0,1] neg_hi:[0,0,1]
	v_pk_fma_f32 v[62:63], v[62:63], v[68:69], v[108:109] op_sel_hi:[1,0,1] neg_lo:[0,0,1] neg_hi:[0,0,1]
	v_pk_fma_f32 v[60:61], v[60:61], v[68:69], v[106:107] op_sel_hi:[1,0,1] neg_lo:[0,0,1] neg_hi:[0,0,1]
	v_pk_fma_f32 v[56:57], v[34:35], v[68:69], v[112:113] op_sel_hi:[1,0,1] neg_lo:[0,0,1] neg_hi:[0,0,1]
	v_pk_fma_f32 v[58:59], v[32:33], v[68:69], v[110:111] op_sel_hi:[1,0,1] neg_lo:[0,0,1] neg_hi:[0,0,1]
	v_pk_fma_f32 v[50:51], v[38:39], v[68:69], v[116:117] op_sel_hi:[1,0,1] neg_lo:[0,0,1] neg_hi:[0,0,1]
	v_pk_fma_f32 v[54:55], v[36:37], v[68:69], v[114:115] op_sel_hi:[1,0,1] neg_lo:[0,0,1] neg_hi:[0,0,1]
	v_pk_fma_f32 v[42:43], v[42:43], v[68:69], v[120:121] op_sel_hi:[1,0,1] neg_lo:[0,0,1] neg_hi:[0,0,1]
	v_pk_fma_f32 v[52:53], v[40:41], v[68:69], v[118:119] op_sel_hi:[1,0,1] neg_lo:[0,0,1] neg_hi:[0,0,1]
	v_pk_fma_f32 v[40:41], v[46:47], v[68:69], v[124:125] op_sel_hi:[1,0,1] neg_lo:[0,0,1] neg_hi:[0,0,1]
	v_pk_fma_f32 v[44:45], v[44:45], v[68:69], v[122:123] op_sel_hi:[1,0,1] neg_lo:[0,0,1] neg_hi:[0,0,1]
	v_pk_fma_f32 v[36:37], v[18:19], v[68:69], v[134:135] op_sel_hi:[1,0,1] neg_lo:[0,0,1] neg_hi:[0,0,1]
	v_pk_fma_f32 v[38:39], v[16:17], v[68:69], v[126:127] op_sel_hi:[1,0,1] neg_lo:[0,0,1] neg_hi:[0,0,1]
	v_pk_fma_f32 v[32:33], v[22:23], v[68:69], v[138:139] op_sel_hi:[1,0,1] neg_lo:[0,0,1] neg_hi:[0,0,1]
	v_pk_fma_f32 v[34:35], v[20:21], v[68:69], v[136:137] op_sel_hi:[1,0,1] neg_lo:[0,0,1] neg_hi:[0,0,1]
	v_pk_fma_f32 v[22:23], v[26:27], v[68:69], v[140:141] op_sel_hi:[1,0,1] neg_lo:[0,0,1] neg_hi:[0,0,1]
	v_pk_fma_f32 v[26:27], v[24:25], v[68:69], v[100:101] op_sel_hi:[1,0,1] neg_lo:[0,0,1] neg_hi:[0,0,1]
	v_pk_fma_f32 v[20:21], v[30:31], v[68:69], v[102:103] op_sel_hi:[1,0,1] neg_lo:[0,0,1] neg_hi:[0,0,1]
; DI float shx(float v, int mask, int lane) { return __int_as_float(__builtin_amdgcn_ds_bpermute(((lane ^ mask) & 63) << 2, __float_as_int(v))); }
; DI void attn_item(const Params& p, int l, int b, int head, int qt, float lam, float lam_init, unsigned char* smem) {
;     ...
;     float ss = 0.f;
; #pragma unroll
;     for (int dt = 0; dt < 4; ++dt)
; #pragma unroll
;       for (int i = 0; i < 16; ++i) {
;         const float o = O[dt][i] * inv - exch[(rg * 64 + dt * 16 + i) * 64 + lane];
;         O[dt][i] = o;
;         ss += o * o;
;       }
;     ss += shx(ss, 32, lane);
;     const float rs = rsqrtf(ss * (1.f / 128.f) + LN_EPS) * (1.f - lam_init);
	v_pk_fma_f32 v[24:25], v[28:29], v[68:69], v[92:93] op_sel_hi:[1,0,1] neg_lo:[0,0,1] neg_hi:[0,0,1]
	v_pk_fma_f32 v[16:17], v[2:3], v[68:69], v[98:99] op_sel_hi:[1,0,1] neg_lo:[0,0,1] neg_hi:[0,0,1]
	v_pk_fma_f32 v[18:19], v[0:1], v[68:69], v[90:91] op_sel_hi:[1,0,1] neg_lo:[0,0,1] neg_hi:[0,0,1]
	v_pk_fma_f32 v[2:3], v[6:7], v[68:69], v[88:89] op_sel_hi:[1,0,1] neg_lo:[0,0,1] neg_hi:[0,0,1]
	v_pk_fma_f32 v[6:7], v[4:5], v[68:69], v[80:81] op_sel_hi:[1,0,1] neg_lo:[0,0,1] neg_hi:[0,0,1]
	v_pk_fma_f32 v[0:1], v[10:11], v[68:69], v[78:79] op_sel_hi:[1,0,1] neg_lo:[0,0,1] neg_hi:[0,0,1]
	v_pk_fma_f32 v[4:5], v[8:9], v[68:69], v[72:73] op_sel_hi:[1,0,1] neg_lo:[0,0,1] neg_hi:[0,0,1]
	v_add_f32_e32 v68, v144, v145
	v_add_f32_e32 v68, v68, v142
	v_pk_mul_f32 v[132:133], v[94:95], v[94:95]
	v_add_f32_e32 v68, v68, v143
	v_add_f32_e32 v68, v68, v132
	v_lshl_add_u64 v[48:49], v[128:129], 0, v[178:179]
	v_pk_mul_f32 v[128:129], v[86:87], v[86:87]
	v_add_f32_e32 v68, v68, v133
	v_add_f32_e32 v68, v68, v128
	v_pk_mul_f32 v[146:147], v[96:97], v[96:97]
	v_add_f32_e32 v68, v68, v129
	v_add_f32_e32 v68, v68, v146
	v_pk_mul_f32 v[104:105], v[76:77], v[76:77]
	v_add_f32_e32 v68, v68, v147
	v_add_f32_e32 v68, v68, v104
	v_pk_mul_f32 v[106:107], v[60:61], v[60:61]
	v_add_f32_e32 v68, v68, v105
	v_add_f32_e32 v68, v68, v106
	v_pk_mul_f32 v[108:109], v[62:63], v[62:63]
	v_add_f32_e32 v68, v68, v107
	v_add_f32_e32 v68, v68, v108
	v_pk_mul_f32 v[110:111], v[58:59], v[58:59]
	v_add_f32_e32 v68, v68, v109
	v_add_f32_e32 v68, v68, v110
	v_pk_mul_f32 v[112:113], v[56:57], v[56:57]
	v_add_f32_e32 v68, v68, v111
	v_add_f32_e32 v68, v68, v112
	v_pk_mul_f32 v[114:115], v[54:55], v[54:55]
	v_add_f32_e32 v68, v68, v113
	v_add_f32_e32 v68, v68, v114
	v_pk_mul_f32 v[116:117], v[50:51], v[50:51]
	v_add_f32_e32 v68, v68, v115
	v_add_f32_e32 v68, v68, v116
	v_pk_mul_f32 v[118:119], v[52:53], v[52:53]
	v_add_f32_e32 v68, v68, v117
	v_add_f32_e32 v68, v68, v118
	v_pk_mul_f32 v[120:121], v[42:43], v[42:43]
	v_add_f32_e32 v68, v68, v119
	v_add_f32_e32 v68, v68, v120
	v_pk_mul_f32 v[122:123], v[44:45], v[44:45]
	v_add_f32_e32 v68, v68, v121
	v_add_f32_e32 v68, v68, v122
	v_pk_mul_f32 v[46:47], v[40:41], v[40:41]
	v_add_f32_e32 v68, v68, v123
	v_add_f32_e32 v46, v68, v46
	v_pk_mul_f32 v[126:127], v[38:39], v[38:39]
	v_add_f32_e32 v46, v46, v47
	v_add_f32_e32 v46, v46, v126
	v_pk_mul_f32 v[124:125], v[36:37], v[36:37]
	v_add_f32_e32 v46, v46, v127
	v_add_f32_e32 v46, v46, v124
	v_pk_mul_f32 v[136:137], v[34:35], v[34:35]
	v_add_f32_e32 v46, v46, v125
	v_add_f32_e32 v46, v46, v136
	v_pk_mul_f32 v[134:135], v[32:33], v[32:33]
	v_add_f32_e32 v46, v46, v137
	v_add_f32_e32 v46, v46, v134
	v_pk_mul_f32 v[100:101], v[26:27], v[26:27]
	v_add_f32_e32 v46, v46, v135
	v_add_f32_e32 v46, v46, v100
	v_pk_mul_f32 v[138:139], v[22:23], v[22:23]
	v_add_f32_e32 v46, v46, v101
	v_add_f32_e32 v46, v46, v138
	v_pk_mul_f32 v[28:29], v[24:25], v[24:25]
	v_add_f32_e32 v46, v46, v139
	v_add_f32_e32 v28, v46, v28
	v_pk_mul_f32 v[30:31], v[20:21], v[20:21]
	v_add_f32_e32 v28, v28, v29
	v_add_f32_e32 v28, v28, v30
	v_pk_mul_f32 v[90:91], v[18:19], v[18:19]
	v_add_f32_e32 v28, v28, v31
	v_add_f32_e32 v28, v28, v90
	v_pk_mul_f32 v[92:93], v[16:17], v[16:17]
	v_add_f32_e32 v28, v28, v91
	v_add_f32_e32 v28, v28, v92
	v_pk_mul_f32 v[80:81], v[6:7], v[6:7]
	v_add_f32_e32 v28, v28, v93
	v_add_f32_e32 v28, v28, v80
	v_pk_mul_f32 v[88:89], v[2:3], v[2:3]
	v_add_f32_e32 v28, v28, v81
	v_add_f32_e32 v28, v28, v88
	v_pk_mul_f32 v[8:9], v[4:5], v[4:5]
	v_add_f32_e32 v28, v28, v89
	v_add_f32_e32 v8, v28, v8
	v_pk_mul_f32 v[10:11], v[0:1], v[0:1]
	v_add_f32_e32 v8, v8, v9
	v_add_f32_e32 v8, v8, v10
	v_add_f32_e32 v8, v8, v11
	v_add_f32_e32 v8, v8, v70
	v_pk_mul_f32 v[82:83], v[66:67], v[66:67]
	v_add_f32_e32 v8, v8, v71
	v_add_f32_e32 v8, v8, v82
	v_add_f32_e32 v8, v8, v83
	ds_bpermute_b32 v9, v131, v8
	s_waitcnt lgkmcnt(0)
	v_add_f32_e32 v8, v8, v9
	v_fmamk_f32 v8, v8, 0x3c000000, v217
	v_cmp_gt_f32_e32 vcc, s4, v8
	v_mul_f32_e32 v9, 0x4b800000, v8
	s_nop 0
	v_cndmask_b32_e32 v8, v8, v9, vcc
	v_rsq_f32_e32 v8, v8
	s_nop 0
	v_mul_f32_e32 v9, 0x45800000, v8
	v_cndmask_b32_e32 v8, v8, v9, vcc
	v_mul_f32_e32 v8, v233, v8
	v_pk_mul_f32 v[10:11], v[84:85], v[8:9] op_sel_hi:[1,0]
	v_pk_mul_f32 v[6:7], v[6:7], v[8:9] op_sel_hi:[1,0]
	s_waitcnt vmcnt(0)
; DI void attn_item(const Params& p, int l, int b, int head, int qt, float lam, float lam_init, unsigned char* smem) {
;     ...
;     u16* AN = (u16*)(p.ws + WS_AN) + (size_t)(qtok0 + rg * 32 + r) * 512 + head * 128;
;     const float* gw = p.in[17] + l * 512 + head * 128;
; #pragma unroll
;     for (int dt = 0; dt < 4; ++dt)
; #pragma unroll
;       for (int g = 0; g < 4; ++g) {
;         const int dv = dt * 32 + 8 * g + 4 * h;
;         const float4 g4 = *(const float4*)(gw + dv);
;         uint2 o;
;         o.x = pack2(O[dt][4 * g] * rs * g4.x, O[dt][4 * g + 1] * rs * g4.y);
;         o.y = pack2(O[dt][4 * g + 2] * rs * g4.z, O[dt][4 * g + 3] * rs * g4.w);
;         *(uint2*)(AN + dv) = o;
;       }
	v_pk_mul_f32 v[10:11], v[12:13], v[10:11]
	v_pk_mul_f32 v[12:13], v[74:75], v[8:9] op_sel_hi:[1,0]
	v_cvt_pk_bf16_f32 v10, v10, v11
	v_pk_mul_f32 v[12:13], v[14:15], v[12:13]
	v_pk_mul_f32 v[14:15], v[94:95], v[8:9] op_sel_hi:[1,0]
	v_cvt_pk_bf16_f32 v11, v12, v13
	global_store_dwordx2 v[48:49], v[10:11], off
	v_mov_b64_e32 v[10:11], v[148:149]
	v_mov_b64_e32 v[12:13], v[150:151]
	global_load_dwordx4 v[148:151], v69, s[2:3] offset:288
	v_pk_mul_f32 v[2:3], v[2:3], v[8:9] op_sel_hi:[1,0]
	v_pk_mul_f32 v[0:1], v[0:1], v[8:9] op_sel_hi:[1,0]
	v_pk_mul_f32 v[10:11], v[10:11], v[14:15]
	v_pk_mul_f32 v[14:15], v[86:87], v[8:9] op_sel_hi:[1,0]
	v_cvt_pk_bf16_f32 v10, v10, v11
	v_pk_mul_f32 v[12:13], v[12:13], v[14:15]
	v_pk_mul_f32 v[14:15], v[96:97], v[8:9] op_sel_hi:[1,0]
	v_cvt_pk_bf16_f32 v11, v12, v13
	global_store_dwordx2 v[48:49], v[10:11], off offset:16
	v_mov_b64_e32 v[10:11], v[152:153]
	v_mov_b64_e32 v[12:13], v[154:155]
	global_load_dwordx4 v[152:155], v69, s[2:3] offset:320
	v_pk_mul_f32 v[10:11], v[14:15], v[10:11]
	v_pk_mul_f32 v[14:15], v[76:77], v[8:9] op_sel_hi:[1,0]
	v_cvt_pk_bf16_f32 v10, v10, v11
	v_pk_mul_f32 v[12:13], v[14:15], v[12:13]
	v_pk_mul_f32 v[14:15], v[60:61], v[8:9] op_sel_hi:[1,0]
	v_cvt_pk_bf16_f32 v11, v12, v13
	global_store_dwordx2 v[48:49], v[10:11], off offset:32
	v_mov_b64_e32 v[10:11], v[156:157]
	v_mov_b64_e32 v[12:13], v[158:159]
	global_load_dwordx4 v[156:159], v69, s[2:3] offset:352
	v_pk_mul_f32 v[10:11], v[14:15], v[10:11]
	v_pk_mul_f32 v[14:15], v[62:63], v[8:9] op_sel_hi:[1,0]
	v_cvt_pk_bf16_f32 v10, v10, v11
	v_pk_mul_f32 v[12:13], v[14:15], v[12:13]
	v_pk_mul_f32 v[14:15], v[58:59], v[8:9] op_sel_hi:[1,0]
	v_cvt_pk_bf16_f32 v11, v12, v13
	global_store_dwordx2 v[48:49], v[10:11], off offset:48
	v_mov_b64_e32 v[10:11], v[160:161]
	v_mov_b64_e32 v[12:13], v[162:163]
	global_load_dwordx4 v[160:163], v69, s[2:3] offset:384
	v_pk_mul_f32 v[10:11], v[14:15], v[10:11]
	v_pk_mul_f32 v[14:15], v[56:57], v[8:9] op_sel_hi:[1,0]
	v_cvt_pk_bf16_f32 v10, v10, v11
	v_pk_mul_f32 v[12:13], v[14:15], v[12:13]
	v_pk_mul_f32 v[14:15], v[54:55], v[8:9] op_sel_hi:[1,0]
	v_cvt_pk_bf16_f32 v11, v12, v13
	global_store_dwordx2 v[48:49], v[10:11], off offset:64
	v_mov_b64_e32 v[10:11], v[164:165]
	v_mov_b64_e32 v[12:13], v[166:167]
	global_load_dwordx4 v[164:167], v69, s[2:3] offset:416
	v_pk_mul_f32 v[10:11], v[14:15], v[10:11]
	v_pk_mul_f32 v[14:15], v[50:51], v[8:9] op_sel_hi:[1,0]
	v_cvt_pk_bf16_f32 v10, v10, v11
	v_pk_mul_f32 v[12:13], v[14:15], v[12:13]
	v_pk_mul_f32 v[14:15], v[52:53], v[8:9] op_sel_hi:[1,0]
	v_cvt_pk_bf16_f32 v11, v12, v13
	global_store_dwordx2 v[48:49], v[10:11], off offset:80
	v_mov_b64_e32 v[10:11], v[168:169]
	v_mov_b64_e32 v[12:13], v[170:171]
	global_load_dwordx4 v[168:171], v69, s[2:3] offset:448
	v_pk_mul_f32 v[10:11], v[14:15], v[10:11]
	v_pk_mul_f32 v[14:15], v[42:43], v[8:9] op_sel_hi:[1,0]
	v_cvt_pk_bf16_f32 v10, v10, v11
	v_pk_mul_f32 v[12:13], v[14:15], v[12:13]
	v_pk_mul_f32 v[14:15], v[44:45], v[8:9] op_sel_hi:[1,0]
	v_cvt_pk_bf16_f32 v11, v12, v13
	global_store_dwordx2 v[48:49], v[10:11], off offset:96
	v_mov_b64_e32 v[10:11], v[244:245]
	v_mov_b64_e32 v[12:13], v[246:247]
	global_load_dwordx4 v[244:247], v69, s[2:3] offset:480
	v_pk_mul_f32 v[10:11], v[14:15], v[10:11]
	v_pk_mul_f32 v[14:15], v[40:41], v[8:9] op_sel_hi:[1,0]
	v_cvt_pk_bf16_f32 v10, v10, v11
	v_pk_mul_f32 v[12:13], v[14:15], v[12:13]
	v_pk_mul_f32 v[14:15], v[38:39], v[8:9] op_sel_hi:[1,0]
	v_cvt_pk_bf16_f32 v11, v12, v13
	global_store_dwordx2 v[48:49], v[10:11], off offset:112
	v_mov_b64_e32 v[10:11], v[248:249]
	v_mov_b64_e32 v[12:13], v[250:251]
	v_pk_mul_f32 v[10:11], v[14:15], v[10:11]
	v_pk_mul_f32 v[14:15], v[36:37], v[8:9] op_sel_hi:[1,0]
	v_cvt_pk_bf16_f32 v10, v10, v11
	v_pk_mul_f32 v[12:13], v[14:15], v[12:13]
	v_pk_mul_f32 v[14:15], v[34:35], v[8:9] op_sel_hi:[1,0]
	v_cvt_pk_bf16_f32 v11, v12, v13
	global_store_dwordx2 v[48:49], v[10:11], off offset:128
	s_waitcnt vmcnt(14)
	v_mov_b64_e32 v[10:11], v[148:149]
	v_mov_b64_e32 v[12:13], v[150:151]
	v_pk_mul_f32 v[10:11], v[14:15], v[10:11]
	v_pk_mul_f32 v[14:15], v[32:33], v[8:9] op_sel_hi:[1,0]
	v_cvt_pk_bf16_f32 v10, v10, v11
	v_pk_mul_f32 v[12:13], v[14:15], v[12:13]
	v_pk_mul_f32 v[14:15], v[26:27], v[8:9] op_sel_hi:[1,0]
	v_cvt_pk_bf16_f32 v11, v12, v13
	global_store_dwordx2 v[48:49], v[10:11], off offset:144
	s_waitcnt vmcnt(13)
	v_mov_b64_e32 v[10:11], v[152:153]
	v_mov_b64_e32 v[12:13], v[154:155]
	v_pk_mul_f32 v[10:11], v[14:15], v[10:11]
	v_pk_mul_f32 v[14:15], v[22:23], v[8:9] op_sel_hi:[1,0]
	v_cvt_pk_bf16_f32 v10, v10, v11
	v_pk_mul_f32 v[12:13], v[14:15], v[12:13]
	v_pk_mul_f32 v[14:15], v[24:25], v[8:9] op_sel_hi:[1,0]
	v_cvt_pk_bf16_f32 v11, v12, v13
	global_store_dwordx2 v[48:49], v[10:11], off offset:160
	s_waitcnt vmcnt(12)
	v_mov_b64_e32 v[10:11], v[156:157]
	v_mov_b64_e32 v[12:13], v[158:159]
	v_pk_mul_f32 v[10:11], v[14:15], v[10:11]
	v_pk_mul_f32 v[14:15], v[20:21], v[8:9] op_sel_hi:[1,0]
	v_cvt_pk_bf16_f32 v10, v10, v11
	v_pk_mul_f32 v[12:13], v[14:15], v[12:13]
	v_pk_mul_f32 v[14:15], v[18:19], v[8:9] op_sel_hi:[1,0]
	v_cvt_pk_bf16_f32 v11, v12, v13
	global_store_dwordx2 v[48:49], v[10:11], off offset:176
	s_waitcnt vmcnt(11)
	v_mov_b64_e32 v[10:11], v[160:161]
	v_mov_b64_e32 v[12:13], v[162:163]
	v_pk_mul_f32 v[10:11], v[14:15], v[10:11]
	v_pk_mul_f32 v[14:15], v[16:17], v[8:9] op_sel_hi:[1,0]
	v_cvt_pk_bf16_f32 v10, v10, v11
	v_pk_mul_f32 v[12:13], v[14:15], v[12:13]
	s_nop 0
	v_cvt_pk_bf16_f32 v11, v12, v13
	global_store_dwordx2 v[48:49], v[10:11], off offset:192
	s_waitcnt vmcnt(10)
	v_mov_b64_e32 v[10:11], v[164:165]
	v_mov_b64_e32 v[12:13], v[166:167]
	v_pk_mul_f32 v[6:7], v[6:7], v[10:11]
	v_pk_mul_f32 v[2:3], v[2:3], v[12:13]
	v_cvt_pk_bf16_f32 v6, v6, v7
	v_cvt_pk_bf16_f32 v7, v2, v3
	global_store_dwordx2 v[48:49], v[6:7], off offset:208
	s_waitcnt vmcnt(9)
	v_mov_b64_e32 v[10:11], v[168:169]
	v_mov_b64_e32 v[12:13], v[170:171]
	v_pk_mul_f32 v[2:3], v[4:5], v[8:9] op_sel_hi:[1,0]
	v_pk_mul_f32 v[4:5], v[64:65], v[8:9] op_sel_hi:[1,0]
	v_pk_mul_f32 v[2:3], v[2:3], v[10:11]
	v_pk_mul_f32 v[0:1], v[0:1], v[12:13]
	v_cvt_pk_bf16_f32 v2, v2, v3
	v_cvt_pk_bf16_f32 v3, v0, v1
	global_store_dwordx2 v[48:49], v[2:3], off offset:224
	s_waitcnt vmcnt(8)
	v_mov_b64_e32 v[0:1], v[244:245]
	v_mov_b64_e32 v[2:3], v[246:247]
	v_pk_mul_f32 v[0:1], v[4:5], v[0:1]
	v_pk_mul_f32 v[4:5], v[66:67], v[8:9] op_sel_hi:[1,0]
	v_cvt_pk_bf16_f32 v0, v0, v1
	v_pk_mul_f32 v[2:3], v[4:5], v[2:3]
	s_nop 0
	v_cvt_pk_bf16_f32 v1, v2, v3
	global_store_dwordx2 v[48:49], v[0:1], off offset:240

; DI int otid() { int t = threadIdx.x; asm volatile("" : "+v"(t)); return t; }
; DI void gbar(unsigned* ctl, unsigned& k) {
;   __syncthreads();
;   ++k;
;   if (otid() == 0) {
;     __threadfence();
;     const unsigned x = blockIdx.x & 7;
;     const unsigned gsz = (gridDim.x + 7 - x) >> 3;
;     const unsigned ngroups = gridDim.x < 8 ? gridDim.x : 8;
;     unsigned* gc = ctl + 64 + x * 32;
;     unsigned* gl = ctl + 32;
;     const unsigned old = __hip_atomic_fetch_add(gc, 1u, __ATOMIC_RELAXED, __HIP_MEMORY_SCOPE_AGENT);
;     if (old + 1 == k * gsz) {
;       __threadfence();
;       __hip_atomic_fetch_add(gl, 1u, __ATOMIC_RELAXED, __HIP_MEMORY_SCOPE_AGENT);
;     }
.LBB0_595:
	v_mov_b32_e32 v0, v212
	s_waitcnt lgkmcnt(0)
	s_barrier
	s_nop 0
	v_cmp_eq_u32_e32 vcc, 0, v0
	s_mov_b64 s[0:1], exec
	s_and_b64 s[2:3], s[0:1], vcc
	v_mov_b32_e32 v210, 0x8040000
	s_mov_b64 exec, s[2:3]
	s_cbranch_execz .LBB0_603
	buffer_wbl2 sc1
	s_waitcnt vmcnt(0)
	buffer_inv sc1
	global_atomic_add v0, v[176:177], v221, off sc0
	v_readlane_b32 s2, v254, 1
	s_add_i32 s6, s2, 2
	v_mul_lo_u32 v1, s6, v213
	s_waitcnt vmcnt(0)
	v_add_u32_e32 v0, 1, v0
	v_cmp_eq_u32_e32 vcc, v0, v1
	s_and_saveexec_b64 s[2:3], vcc
	s_cbranch_execz .LBB0_599
	s_mov_b64 s[4:5], exec
	v_mbcnt_lo_u32_b32 v0, s4, 0
	v_mbcnt_hi_u32_b32 v0, s5, v0
	v_cmp_eq_u32_e32 vcc, 0, v0
	s_and_b64 s[8:9], exec, vcc
	s_mov_b64 exec, s[8:9]
	s_cbranch_execz .LBB0_599
	s_bcnt1_i32_b64 s4, s[4:5]
	v_mov_b32_e32 v0, s4
	v_readlane_b32 s4, v253, 10
	v_readlane_b32 s5, v253, 11
	s_nop 4
	global_atomic_add v179, v0, s[4:5]

; DI int otid() { int t = threadIdx.x; asm volatile("" : "+v"(t)); return t; }
; template <class PF, class EF>
; DI void gemm_stream(int lda, int ldw, int K, unsigned char* smem, PF ptrs, EF epi) {
;   const int tid = otid(), lane = tid & 63, w = tid >> 6;
;   const int wm = w >> 2, wn = w & 3, r = lane & 31, h = lane >> 5;
;   unsigned char* sbase = smem + GS_BASE;
;   constexpr int SLOT = 512 * 64;
;   const int nh = K >> 5;
;   const int c0 = (h ^ ((r >> 2) & 3)) * 16, c1 = c0 ^ 32;
;   const int aoff = (wm * 128 + r) * 64, boff = (256 + wn * 64 + r) * 64;
;   const int lr16 = lane >> 2, lchunk = (lane & 3) ^ ((lane >> 4) & 3);
;   const int wu = __builtin_amdgcn_readfirstlane(w);
;   const bool isB = wu >= 4;
;   const unsigned goff = isB ? (unsigned)((((wu - 4) * 64 + 2 * lr16) * ldw + lchunk * 8) * 2)
;                             : (unsigned)(((wu * 64 + lr16) * lda + lchunk * 8) * 2);
; DI void gbar(unsigned* ctl, unsigned& k) {
;     ...
;     while (__hip_atomic_load(gl, __ATOMIC_RELAXED, __HIP_MEMORY_SCOPE_AGENT) < k * ngroups) __builtin_amdgcn_s_sleep(1);
;     __threadfence();
;   }
;   __syncthreads();
.LBB0_601:
	s_sleep 1
	global_load_dword v1, v179, s[4:5] sc1
	s_waitcnt vmcnt(0)
	v_cmp_ge_u32_e32 vcc, v1, v0
	s_or_b64 s[2:3], vcc, s[2:3]
	s_andn2_b64 exec, exec, s[2:3]
	s_cbranch_execnz .LBB0_601
.LBB0_602:
	buffer_inv sc1
.LBB0_603:
	s_or_b64 exec, exec, s[0:1]
	v_mov_b32_e32 v0, v212
	s_barrier
	s_mov_b64 s[2:3], -1
	v_mov_b32_e32 v0, v212
	s_nop 0
	v_readfirstlane_b32 s5, v0
	v_lshrrev_b32_e32 v2, 4, v0
	s_ashr_i32 s4, s5, 6
	v_bitop3_b32 v2, v2, 3, v0 bitop3:0x48
	s_cmp_gt_i32 s4, 3
	v_bfe_u32 v1, v0, 2, 4
	s_cselect_b64 s[0:1], -1, 0
	s_cmp_lt_i32 s4, 4
	v_lshlrev_b32_e32 v2, 4, v2
	s_cbranch_scc0 .LBB0_605
	s_and_b32 s2, s5, 0x3fffc0
	v_or_b32_e32 v3, s2, v1
	v_lshl_or_b32 v178, v3, 10, v2
	s_mov_b64 s[2:3], 0

; DI float bflo(unsigned v) { return __uint_as_float(v << 16); }
; DI float bfhi(unsigned v) { return __uint_as_float(v & 0xffff0000u); }
; DI void phase_mix(const Params& p, int l, unsigned char* smem) {
;     ...
;     for (int mi = 0; mi < 4; ++mi) {
;       if (mi > 0) __syncthreads();
;       stage_rm(acc[mi][0], acc[mi][1], stg, wm, wn, r, h);
;       __syncthreads();
; #pragma unroll 1
;       for (int q = 0; q < 4; ++q) {
;         const int cid = q * NTHR + tid, lr = cid >> 5, c8 = (cid & 31) * 8;
;         const float4 v0 = *(const float4*)(stg + lr * EP_LD + c8);
;         const float4 v1 = *(const float4*)(stg + lr * EP_LD + c8 + 4);
;         const int row = grow_of(m0, mi, lr), n = n0 + c8;
;         const uint4 g = *(const uint4*)(G + (size_t)row * 2048 + half * 1024 + n);
;         float4 o0 = make_float4(bflo(g.x) * v0.x, bfhi(g.x) * v0.y, bflo(g.y) * v0.z, bfhi(g.y) * v0.w);
;         float4 o1 = make_float4(bflo(g.z) * v1.x, bfhi(g.z) * v1.y, bflo(g.w) * v1.z, bfhi(g.w) * v1.w);
;         uint4* mp = (uint4*)(MIX + (size_t)row * 1024 + n);
;         if (half) {
;           const uint4 pr = *mp;
;           o0.x += bflo(pr.x); o0.y += bfhi(pr.x); o0.z += bflo(pr.y); o0.w += bfhi(pr.y);
;           o1.x += bflo(pr.z); o1.y += bfhi(pr.z); o1.z += bflo(pr.w); o1.w += bfhi(pr.w);
;         }
;         *mp = pack8f(o0, o1);
;       }
.LBB0_643:
	s_or_b64 exec, exec, s[16:17]
	v_lshrrev_b32_e32 v132, 3, v128
	v_and_b32_e32 v134, 0x7ffffe4, v132
	v_lshlrev_b32_e32 v132, 3, v128
	s_and_b64 s[6:7], exec, vcc
	v_and_b32_e32 v131, 0xc0, v128
	v_and_b32_e32 v136, 0xf8, v132
	s_or_b64 s[14:15], s[6:7], s[14:15]
	v_or_b32_e32 v132, v130, v136
	v_lshlrev_b32_e32 v130, 2, v131
	v_readlane_b32 s7, v254, 2
	v_mul_lo_u32 v131, v134, s85
	v_mov_b32_e32 v134, v96
	v_add3_u32 v130, s7, v130, v136
	v_add_u32_e32 v130, v130, v131
	v_mov_b32_e32 v135, v112
	v_mov_b32_e32 v112, v97
	s_waitcnt vmcnt(0)
	ds_write2_b64 v130, v[134:135], v[112:113] offset1:132
	v_mov_b32_e32 v112, v98
	v_mov_b32_e32 v113, v114
	v_mov_b32_e32 v114, v99
	v_add_u32_e32 v97, 0x800, v130
	ds_write2_b64 v97, v[112:113], v[114:115] offset0:8 offset1:140
	v_mov_b32_e32 v98, v100
	v_mov_b32_e32 v99, v116
	v_mov_b32_e32 v116, v101
	v_add_u32_e32 v112, 0x2000, v130
	s_and_b32 s6, s31, 1
	ds_write2_b64 v112, v[98:99], v[116:117] offset0:32 offset1:164
	v_mov_b32_e32 v98, v102
	v_mov_b32_e32 v99, v118
	v_mov_b32_e32 v118, v103
	v_add_u32_e32 v113, 0x2800, v130
	s_bitcmp1_b32 s31, 0
	ds_write2_b64 v113, v[98:99], v[118:119] offset0:40 offset1:172
	v_mov_b32_e32 v98, v104
	v_mov_b32_e32 v99, v120
	v_mov_b32_e32 v120, v105
	v_add_u32_e32 v114, 0x4000, v130
	s_cselect_b64 s[16:17], -1, 0
	ds_write2_b64 v114, v[98:99], v[120:121] offset0:64 offset1:196
	v_mov_b32_e32 v98, v106
	v_mov_b32_e32 v99, v122
	v_mov_b32_e32 v122, v107
	v_add_u32_e32 v115, 0x4800, v130
	s_lshl_b32 s6, s6, 11
	v_readlane_b32 s34, v252, 58
	v_ashrrev_i32_e32 v133, 31, v132
	ds_write2_b64 v115, v[98:99], v[122:123] offset0:72 offset1:204
	v_mov_b32_e32 v98, v108
	v_mov_b32_e32 v99, v124
	v_mov_b32_e32 v124, v109
	v_add_u32_e32 v116, 0x6000, v130
	v_readlane_b32 s35, v252, 59
	s_add_u32 s6, s34, s6
	ds_write2_b64 v116, v[98:99], v[124:125] offset0:96 offset1:228
	v_mov_b32_e32 v98, v110
	v_mov_b32_e32 v99, v126
	v_mov_b32_e32 v126, v111
	v_add_u32_e32 v117, 0x6800, v130
	v_lshl_add_u32 v96, v136, 2, s7
	s_addc_u32 s7, s35, 0
	v_lshlrev_b64 v[100:101], 1, v[132:133]
	ds_write2_b64 v117, v[98:99], v[126:127] offset0:104 offset1:236
	v_lshl_add_u64 v[98:99], s[6:7], 0, v[100:101]
	v_readlane_b32 s6, v252, 62
	v_readlane_b32 s7, v252, 63
	s_mov_b32 s19, 0
	s_waitcnt lgkmcnt(0)
	v_lshl_add_u64 v[100:101], s[6:7], 0, v[100:101]
	s_barrier
	s_mov_b64 s[36:37], s[16:17]
	v_lshrrev_b32_e32 v137, 5, v128
	v_mad_u32_u24 v216, v137, s85, v96
	v_add_u32_e32 v137, v137, v129
	s_mov_b32 s38, 0x10000
	s_mov_b32 s39, 0
	s_mov_b32 s40, 0x70000
	s_mov_b32 s41, 0
	s_mov_b32 s42, 0x8000
	s_mov_b32 s43, 0
	s_mov_b32 s44, 0x38000
	s_mov_b32 s45, 0
	v_lshlrev_b32_e32 v102, 12, v137
	v_mov_b32_e32 v103, 0
	v_lshlrev_b32_e32 v108, 11, v137
	v_mov_b32_e32 v109, 0
	v_lshl_add_u64 v[102:103], v[102:103], 0, v[98:99]
	v_lshl_add_u64 v[108:109], v[108:109], 0, v[100:101]
	global_load_dwordx4 v[138:141], v[102:103], off
	v_lshl_add_u64 v[102:103], v[102:103], 0, s[38:39]
	global_load_dwordx4 v[142:145], v[102:103], off
	v_lshl_add_u64 v[102:103], v[102:103], 0, s[40:41]
	global_load_dwordx4 v[146:149], v[102:103], off
	v_lshl_add_u64 v[102:103], v[102:103], 0, s[38:39]
	global_load_dwordx4 v[150:153], v[102:103], off
	s_cmp_lg_u64 s[36:37], 0
	s_cbranch_scc0 .Lmx_m0_np
	v_mov_b32_e32 v102, v108
	v_mov_b32_e32 v103, v109
	global_load_dwordx4 v[154:157], v[102:103], off
	v_lshl_add_u64 v[102:103], v[102:103], 0, s[42:43]
	global_load_dwordx4 v[158:161], v[102:103], off
	v_lshl_add_u64 v[102:103], v[102:103], 0, s[44:45]
	global_load_dwordx4 v[162:165], v[102:103], off
	v_lshl_add_u64 v[102:103], v[102:103], 0, s[42:43]
	global_load_dwordx4 v[166:169], v[102:103], off
.Lmx_m0_np:
	ds_read_b128 v[170:173], v216
	ds_read_b128 v[244:247], v216 offset:16
	ds_read_b128 v[248:251], v216 offset:16896
	ds_read_b128 v[104:107], v216 offset:16912
	s_waitcnt vmcnt(3)
	s_waitcnt lgkmcnt(2)
	v_lshlrev_b32_e32 v232, 16, v138
	v_and_b32_e32 v233, 0xffff0000, v138
	v_pk_mul_f32 v[170:171], v[170:171], v[232:233]
	v_lshlrev_b32_e32 v232, 16, v139
	v_and_b32_e32 v233, 0xffff0000, v139
	v_pk_mul_f32 v[172:173], v[172:173], v[232:233]
	v_lshlrev_b32_e32 v232, 16, v140
	v_and_b32_e32 v233, 0xffff0000, v140
	v_pk_mul_f32 v[244:245], v[244:245], v[232:233]
	v_lshlrev_b32_e32 v232, 16, v141
	v_and_b32_e32 v233, 0xffff0000, v141
	v_pk_mul_f32 v[246:247], v[246:247], v[232:233]
	s_cmp_lg_u64 s[36:37], 0
	s_cbranch_scc0 .Lmx_m0_s0
	v_lshlrev_b32_e32 v232, 16, v154
	v_and_b32_e32 v233, 0xffff0000, v154
	v_pk_add_f32 v[170:171], v[170:171], v[232:233]
	v_lshlrev_b32_e32 v232, 16, v155
	v_and_b32_e32 v233, 0xffff0000, v155
	v_pk_add_f32 v[172:173], v[172:173], v[232:233]
	v_lshlrev_b32_e32 v232, 16, v156
	v_and_b32_e32 v233, 0xffff0000, v156
	v_pk_add_f32 v[244:245], v[244:245], v[232:233]
	v_lshlrev_b32_e32 v232, 16, v157
	v_and_b32_e32 v233, 0xffff0000, v157
	v_pk_add_f32 v[246:247], v[246:247], v[232:233]
.Lmx_m0_s0:
	v_cvt_pk_bf16_f32 v138, v170, v171
	v_cvt_pk_bf16_f32 v139, v172, v173
	v_cvt_pk_bf16_f32 v140, v244, v245
	v_cvt_pk_bf16_f32 v141, v246, v247
	global_store_dwordx4 v[108:109], v[138:141], off
	v_lshl_add_u64 v[108:109], v[108:109], 0, s[42:43]
	ds_read_b128 v[170:173], v216 offset:33792
	ds_read_b128 v[244:247], v216 offset:33808
	s_waitcnt vmcnt(3)
	s_waitcnt lgkmcnt(2)
	v_lshlrev_b32_e32 v232, 16, v142
	v_and_b32_e32 v233, 0xffff0000, v142
	v_pk_mul_f32 v[248:249], v[248:249], v[232:233]
	v_lshlrev_b32_e32 v232, 16, v143
	v_and_b32_e32 v233, 0xffff0000, v143
	v_pk_mul_f32 v[250:251], v[250:251], v[232:233]
	v_lshlrev_b32_e32 v232, 16, v144
	v_and_b32_e32 v233, 0xffff0000, v144
	v_pk_mul_f32 v[104:105], v[104:105], v[232:233]
	v_lshlrev_b32_e32 v232, 16, v145
	v_and_b32_e32 v233, 0xffff0000, v145
	v_pk_mul_f32 v[106:107], v[106:107], v[232:233]
	s_cmp_lg_u64 s[36:37], 0
	s_cbranch_scc0 .Lmx_m0_s1
	v_lshlrev_b32_e32 v232, 16, v158
	v_and_b32_e32 v233, 0xffff0000, v158
	v_pk_add_f32 v[248:249], v[248:249], v[232:233]
	v_lshlrev_b32_e32 v232, 16, v159
	v_and_b32_e32 v233, 0xffff0000, v159
	v_pk_add_f32 v[250:251], v[250:251], v[232:233]
	v_lshlrev_b32_e32 v232, 16, v160
	v_and_b32_e32 v233, 0xffff0000, v160
	v_pk_add_f32 v[104:105], v[104:105], v[232:233]
	v_lshlrev_b32_e32 v232, 16, v161
	v_and_b32_e32 v233, 0xffff0000, v161
	v_pk_add_f32 v[106:107], v[106:107], v[232:233]
; DI float bflo(unsigned v) { return __uint_as_float(v << 16); }
; DI float bfhi(unsigned v) { return __uint_as_float(v & 0xffff0000u); }
; DI void phase_mix(const Params& p, int l, unsigned char* smem) {
;     ...
;     for (int mi = 0; mi < 4; ++mi) {
;       if (mi > 0) __syncthreads();
;       stage_rm(acc[mi][0], acc[mi][1], stg, wm, wn, r, h);
;       __syncthreads();
; #pragma unroll 1
;       for (int q = 0; q < 4; ++q) {
;         const int cid = q * NTHR + tid, lr = cid >> 5, c8 = (cid & 31) * 8;
;         const float4 v0 = *(const float4*)(stg + lr * EP_LD + c8);
;         const float4 v1 = *(const float4*)(stg + lr * EP_LD + c8 + 4);
;         const int row = grow_of(m0, mi, lr), n = n0 + c8;
;         const uint4 g = *(const uint4*)(G + (size_t)row * 2048 + half * 1024 + n);
;         float4 o0 = make_float4(bflo(g.x) * v0.x, bfhi(g.x) * v0.y, bflo(g.y) * v0.z, bfhi(g.y) * v0.w);
;         float4 o1 = make_float4(bflo(g.z) * v1.x, bfhi(g.z) * v1.y, bflo(g.w) * v1.z, bfhi(g.w) * v1.w);
;         uint4* mp = (uint4*)(MIX + (size_t)row * 1024 + n);
;         if (half) {
;           const uint4 pr = *mp;
;           o0.x += bflo(pr.x); o0.y += bfhi(pr.x); o0.z += bflo(pr.y); o0.w += bfhi(pr.y);
;           o1.x += bflo(pr.z); o1.y += bfhi(pr.z); o1.z += bflo(pr.w); o1.w += bfhi(pr.w);
;         }
;         *mp = pack8f(o0, o1);
;       }
.Lmx_m0_s1:
	v_cvt_pk_bf16_f32 v142, v248, v249
	v_cvt_pk_bf16_f32 v143, v250, v251
	v_cvt_pk_bf16_f32 v144, v104, v105
	v_cvt_pk_bf16_f32 v145, v106, v107
	global_store_dwordx4 v[108:109], v[142:145], off
	v_lshl_add_u64 v[108:109], v[108:109], 0, s[44:45]
	ds_read_b128 v[248:251], v216 offset:50688
	ds_read_b128 v[104:107], v216 offset:50704
	s_waitcnt vmcnt(3)
	s_waitcnt lgkmcnt(2)
	v_lshlrev_b32_e32 v232, 16, v146
	v_and_b32_e32 v233, 0xffff0000, v146
	v_pk_mul_f32 v[170:171], v[170:171], v[232:233]
	v_lshlrev_b32_e32 v232, 16, v147
	v_and_b32_e32 v233, 0xffff0000, v147
	v_pk_mul_f32 v[172:173], v[172:173], v[232:233]
	v_lshlrev_b32_e32 v232, 16, v148
	v_and_b32_e32 v233, 0xffff0000, v148
	v_pk_mul_f32 v[244:245], v[244:245], v[232:233]
	v_lshlrev_b32_e32 v232, 16, v149
	v_and_b32_e32 v233, 0xffff0000, v149
	v_pk_mul_f32 v[246:247], v[246:247], v[232:233]
	s_cmp_lg_u64 s[36:37], 0
	s_cbranch_scc0 .Lmx_m0_s2
	v_lshlrev_b32_e32 v232, 16, v162
	v_and_b32_e32 v233, 0xffff0000, v162
	v_pk_add_f32 v[170:171], v[170:171], v[232:233]
	v_lshlrev_b32_e32 v232, 16, v163
	v_and_b32_e32 v233, 0xffff0000, v163
	v_pk_add_f32 v[172:173], v[172:173], v[232:233]
	v_lshlrev_b32_e32 v232, 16, v164
	v_and_b32_e32 v233, 0xffff0000, v164
	v_pk_add_f32 v[244:245], v[244:245], v[232:233]
	v_lshlrev_b32_e32 v232, 16, v165
	v_and_b32_e32 v233, 0xffff0000, v165
	v_pk_add_f32 v[246:247], v[246:247], v[232:233]
.Lmx_m0_s2:
	v_cvt_pk_bf16_f32 v146, v170, v171
	v_cvt_pk_bf16_f32 v147, v172, v173
	v_cvt_pk_bf16_f32 v148, v244, v245
	v_cvt_pk_bf16_f32 v149, v246, v247
	global_store_dwordx4 v[108:109], v[146:149], off
	v_lshl_add_u64 v[108:109], v[108:109], 0, s[42:43]
	s_waitcnt vmcnt(3)
	s_waitcnt lgkmcnt(0)
	v_lshlrev_b32_e32 v232, 16, v150
	v_and_b32_e32 v233, 0xffff0000, v150
	v_pk_mul_f32 v[248:249], v[248:249], v[232:233]
	v_lshlrev_b32_e32 v232, 16, v151
	v_and_b32_e32 v233, 0xffff0000, v151
	v_pk_mul_f32 v[250:251], v[250:251], v[232:233]
	v_lshlrev_b32_e32 v232, 16, v152
	v_and_b32_e32 v233, 0xffff0000, v152
	v_pk_mul_f32 v[104:105], v[104:105], v[232:233]
	v_lshlrev_b32_e32 v232, 16, v153
	v_and_b32_e32 v233, 0xffff0000, v153
	v_pk_mul_f32 v[106:107], v[106:107], v[232:233]
	s_cmp_lg_u64 s[36:37], 0
	s_cbranch_scc0 .Lmx_m0_s3
	v_lshlrev_b32_e32 v232, 16, v166
	v_and_b32_e32 v233, 0xffff0000, v166
	v_pk_add_f32 v[248:249], v[248:249], v[232:233]
	v_lshlrev_b32_e32 v232, 16, v167
	v_and_b32_e32 v233, 0xffff0000, v167
	v_pk_add_f32 v[250:251], v[250:251], v[232:233]
	v_lshlrev_b32_e32 v232, 16, v168
	v_and_b32_e32 v233, 0xffff0000, v168
	v_pk_add_f32 v[104:105], v[104:105], v[232:233]
	v_lshlrev_b32_e32 v232, 16, v169
	v_and_b32_e32 v233, 0xffff0000, v169
	v_pk_add_f32 v[106:107], v[106:107], v[232:233]
.Lmx_m0_s3:
	v_cvt_pk_bf16_f32 v150, v248, v249
	v_cvt_pk_bf16_f32 v151, v250, v251
	v_cvt_pk_bf16_f32 v152, v104, v105
	v_cvt_pk_bf16_f32 v153, v106, v107
	global_store_dwordx4 v[108:109], v[150:153], off
.LBB0_647:
	v_mov_b32_e32 v102, v64
	v_mov_b32_e32 v103, v80
	v_mov_b32_e32 v80, v65
	v_mov_b32_e32 v64, v66
	v_mov_b32_e32 v65, v82
	v_mov_b32_e32 v82, v67
	s_barrier
	ds_write2_b64 v97, v[64:65], v[82:83] offset0:8 offset1:140
	v_mov_b32_e32 v64, v68
	v_mov_b32_e32 v65, v84
	v_mov_b32_e32 v84, v69
	ds_write2_b64 v112, v[64:65], v[84:85] offset0:32 offset1:164
	v_mov_b32_e32 v64, v70
	v_mov_b32_e32 v65, v86
	v_mov_b32_e32 v86, v71
	ds_write2_b64 v113, v[64:65], v[86:87] offset0:40 offset1:172
	v_mov_b32_e32 v64, v72
	v_mov_b32_e32 v65, v88
	v_mov_b32_e32 v88, v73
	ds_write2_b64 v114, v[64:65], v[88:89] offset0:64 offset1:196
	v_mov_b32_e32 v64, v74
	v_mov_b32_e32 v65, v90
	v_mov_b32_e32 v90, v75
	ds_write2_b64 v115, v[64:65], v[90:91] offset0:72 offset1:204
	v_mov_b32_e32 v64, v76
	v_mov_b32_e32 v65, v92
	v_mov_b32_e32 v92, v77
	ds_write2_b64 v116, v[64:65], v[92:93] offset0:96 offset1:228
	v_mov_b32_e32 v64, v78
	v_mov_b32_e32 v65, v94
	v_mov_b32_e32 v94, v79
	v_add_u32_e32 v74, 32, v129
	s_mov_b32 s16, 0
	ds_write2_b64 v130, v[102:103], v[80:81] offset1:132
	ds_write2_b64 v117, v[64:65], v[94:95] offset0:104 offset1:236
	s_waitcnt lgkmcnt(0)
	s_barrier
	v_lshrrev_b32_e32 v137, 5, v128
	v_mad_u32_u24 v216, v137, s85, v96
	v_add_u32_e32 v137, v137, v74
	s_mov_b32 s38, 0x10000
	s_mov_b32 s39, 0
	s_mov_b32 s40, 0x70000
	s_mov_b32 s41, 0
	s_mov_b32 s42, 0x8000
	s_mov_b32 s43, 0
	s_mov_b32 s44, 0x38000
	s_mov_b32 s45, 0
	v_lshlrev_b32_e32 v64, 12, v137
	v_mov_b32_e32 v65, 0
	v_lshlrev_b32_e32 v70, 11, v137
	v_mov_b32_e32 v71, 0
	v_lshl_add_u64 v[64:65], v[64:65], 0, v[98:99]
	v_lshl_add_u64 v[70:71], v[70:71], 0, v[100:101]
	global_load_dwordx4 v[138:141], v[64:65], off
	v_lshl_add_u64 v[64:65], v[64:65], 0, s[38:39]
	global_load_dwordx4 v[142:145], v[64:65], off
	v_lshl_add_u64 v[64:65], v[64:65], 0, s[40:41]
	global_load_dwordx4 v[146:149], v[64:65], off
	v_lshl_add_u64 v[64:65], v[64:65], 0, s[38:39]
	global_load_dwordx4 v[150:153], v[64:65], off
	s_cmp_lg_u64 s[36:37], 0
	s_cbranch_scc0 .Lmx_m1_np
	v_mov_b32_e32 v64, v70
	v_mov_b32_e32 v65, v71
	global_load_dwordx4 v[154:157], v[64:65], off
	v_lshl_add_u64 v[64:65], v[64:65], 0, s[42:43]
	global_load_dwordx4 v[158:161], v[64:65], off
	v_lshl_add_u64 v[64:65], v[64:65], 0, s[44:45]
	global_load_dwordx4 v[162:165], v[64:65], off
	v_lshl_add_u64 v[64:65], v[64:65], 0, s[42:43]
	global_load_dwordx4 v[166:169], v[64:65], off
; DI float bflo(unsigned v) { return __uint_as_float(v << 16); }
; DI float bfhi(unsigned v) { return __uint_as_float(v & 0xffff0000u); }
; DI void phase_mix(const Params& p, int l, unsigned char* smem) {
;     ...
; #pragma unroll 1
;       for (int q = 0; q < 4; ++q) {
;         const int cid = q * NTHR + tid, lr = cid >> 5, c8 = (cid & 31) * 8;
;         const float4 v0 = *(const float4*)(stg + lr * EP_LD + c8);
;         const float4 v1 = *(const float4*)(stg + lr * EP_LD + c8 + 4);
;         const int row = grow_of(m0, mi, lr), n = n0 + c8;
;         const uint4 g = *(const uint4*)(G + (size_t)row * 2048 + half * 1024 + n);
;         float4 o0 = make_float4(bflo(g.x) * v0.x, bfhi(g.x) * v0.y, bflo(g.y) * v0.z, bfhi(g.y) * v0.w);
;         float4 o1 = make_float4(bflo(g.z) * v1.x, bfhi(g.z) * v1.y, bflo(g.w) * v1.z, bfhi(g.w) * v1.w);
;         uint4* mp = (uint4*)(MIX + (size_t)row * 1024 + n);
;         if (half) {
;           const uint4 pr = *mp;
;           o0.x += bflo(pr.x); o0.y += bfhi(pr.x); o0.z += bflo(pr.y); o0.w += bfhi(pr.y);
;           o1.x += bflo(pr.z); o1.y += bfhi(pr.z); o1.z += bflo(pr.w); o1.w += bfhi(pr.w);
;         }
;         *mp = pack8f(o0, o1);
;       }
.Lmx_m1_np:
	ds_read_b128 v[170:173], v216
	ds_read_b128 v[244:247], v216 offset:16
	ds_read_b128 v[248:251], v216 offset:16896
	ds_read_b128 v[66:69], v216 offset:16912
	s_waitcnt vmcnt(3)
	s_waitcnt lgkmcnt(2)
	v_lshlrev_b32_e32 v232, 16, v138
	v_and_b32_e32 v233, 0xffff0000, v138
	v_pk_mul_f32 v[170:171], v[170:171], v[232:233]
	v_lshlrev_b32_e32 v232, 16, v139
	v_and_b32_e32 v233, 0xffff0000, v139
	v_pk_mul_f32 v[172:173], v[172:173], v[232:233]
	v_lshlrev_b32_e32 v232, 16, v140
	v_and_b32_e32 v233, 0xffff0000, v140
	v_pk_mul_f32 v[244:245], v[244:245], v[232:233]
	v_lshlrev_b32_e32 v232, 16, v141
	v_and_b32_e32 v233, 0xffff0000, v141
	v_pk_mul_f32 v[246:247], v[246:247], v[232:233]
	s_cmp_lg_u64 s[36:37], 0
	s_cbranch_scc0 .Lmx_m1_s0
	v_lshlrev_b32_e32 v232, 16, v154
	v_and_b32_e32 v233, 0xffff0000, v154
	v_pk_add_f32 v[170:171], v[170:171], v[232:233]
	v_lshlrev_b32_e32 v232, 16, v155
	v_and_b32_e32 v233, 0xffff0000, v155
	v_pk_add_f32 v[172:173], v[172:173], v[232:233]
	v_lshlrev_b32_e32 v232, 16, v156
	v_and_b32_e32 v233, 0xffff0000, v156
	v_pk_add_f32 v[244:245], v[244:245], v[232:233]
	v_lshlrev_b32_e32 v232, 16, v157
	v_and_b32_e32 v233, 0xffff0000, v157
	v_pk_add_f32 v[246:247], v[246:247], v[232:233]
.Lmx_m1_s0:
	v_cvt_pk_bf16_f32 v138, v170, v171
	v_cvt_pk_bf16_f32 v139, v172, v173
	v_cvt_pk_bf16_f32 v140, v244, v245
	v_cvt_pk_bf16_f32 v141, v246, v247
	global_store_dwordx4 v[70:71], v[138:141], off
	v_lshl_add_u64 v[70:71], v[70:71], 0, s[42:43]
	ds_read_b128 v[170:173], v216 offset:33792
	ds_read_b128 v[244:247], v216 offset:33808
	s_waitcnt vmcnt(3)
	s_waitcnt lgkmcnt(2)
	v_lshlrev_b32_e32 v232, 16, v142
	v_and_b32_e32 v233, 0xffff0000, v142
	v_pk_mul_f32 v[248:249], v[248:249], v[232:233]
	v_lshlrev_b32_e32 v232, 16, v143
	v_and_b32_e32 v233, 0xffff0000, v143
	v_pk_mul_f32 v[250:251], v[250:251], v[232:233]
	v_lshlrev_b32_e32 v232, 16, v144
	v_and_b32_e32 v233, 0xffff0000, v144
	v_pk_mul_f32 v[66:67], v[66:67], v[232:233]
	v_lshlrev_b32_e32 v232, 16, v145
	v_and_b32_e32 v233, 0xffff0000, v145
	v_pk_mul_f32 v[68:69], v[68:69], v[232:233]
	s_cmp_lg_u64 s[36:37], 0
	s_cbranch_scc0 .Lmx_m1_s1
	v_lshlrev_b32_e32 v232, 16, v158
	v_and_b32_e32 v233, 0xffff0000, v158
	v_pk_add_f32 v[248:249], v[248:249], v[232:233]
	v_lshlrev_b32_e32 v232, 16, v159
	v_and_b32_e32 v233, 0xffff0000, v159
	v_pk_add_f32 v[250:251], v[250:251], v[232:233]
	v_lshlrev_b32_e32 v232, 16, v160
	v_and_b32_e32 v233, 0xffff0000, v160
	v_pk_add_f32 v[66:67], v[66:67], v[232:233]
	v_lshlrev_b32_e32 v232, 16, v161
	v_and_b32_e32 v233, 0xffff0000, v161
	v_pk_add_f32 v[68:69], v[68:69], v[232:233]
.Lmx_m1_s1:
	v_cvt_pk_bf16_f32 v142, v248, v249
	v_cvt_pk_bf16_f32 v143, v250, v251
	v_cvt_pk_bf16_f32 v144, v66, v67
	v_cvt_pk_bf16_f32 v145, v68, v69
	global_store_dwordx4 v[70:71], v[142:145], off
	v_lshl_add_u64 v[70:71], v[70:71], 0, s[44:45]
	ds_read_b128 v[248:251], v216 offset:50688
	ds_read_b128 v[66:69], v216 offset:50704
	s_waitcnt vmcnt(3)
	s_waitcnt lgkmcnt(2)
	v_lshlrev_b32_e32 v232, 16, v146
	v_and_b32_e32 v233, 0xffff0000, v146
	v_pk_mul_f32 v[170:171], v[170:171], v[232:233]
	v_lshlrev_b32_e32 v232, 16, v147
	v_and_b32_e32 v233, 0xffff0000, v147
	v_pk_mul_f32 v[172:173], v[172:173], v[232:233]
	v_lshlrev_b32_e32 v232, 16, v148
	v_and_b32_e32 v233, 0xffff0000, v148
	v_pk_mul_f32 v[244:245], v[244:245], v[232:233]
	v_lshlrev_b32_e32 v232, 16, v149
	v_and_b32_e32 v233, 0xffff0000, v149
	v_pk_mul_f32 v[246:247], v[246:247], v[232:233]
	s_cmp_lg_u64 s[36:37], 0
	s_cbranch_scc0 .Lmx_m1_s2
	v_lshlrev_b32_e32 v232, 16, v162
	v_and_b32_e32 v233, 0xffff0000, v162
	v_pk_add_f32 v[170:171], v[170:171], v[232:233]
	v_lshlrev_b32_e32 v232, 16, v163
	v_and_b32_e32 v233, 0xffff0000, v163
	v_pk_add_f32 v[172:173], v[172:173], v[232:233]
	v_lshlrev_b32_e32 v232, 16, v164
	v_and_b32_e32 v233, 0xffff0000, v164
	v_pk_add_f32 v[244:245], v[244:245], v[232:233]
	v_lshlrev_b32_e32 v232, 16, v165
	v_and_b32_e32 v233, 0xffff0000, v165
	v_pk_add_f32 v[246:247], v[246:247], v[232:233]
.Lmx_m1_s2:
	v_cvt_pk_bf16_f32 v146, v170, v171
	v_cvt_pk_bf16_f32 v147, v172, v173
	v_cvt_pk_bf16_f32 v148, v244, v245
	v_cvt_pk_bf16_f32 v149, v246, v247
	global_store_dwordx4 v[70:71], v[146:149], off
	v_lshl_add_u64 v[70:71], v[70:71], 0, s[42:43]
	s_waitcnt vmcnt(3)
	s_waitcnt lgkmcnt(0)
	v_lshlrev_b32_e32 v232, 16, v150
	v_and_b32_e32 v233, 0xffff0000, v150
	v_pk_mul_f32 v[248:249], v[248:249], v[232:233]
	v_lshlrev_b32_e32 v232, 16, v151
	v_and_b32_e32 v233, 0xffff0000, v151
	v_pk_mul_f32 v[250:251], v[250:251], v[232:233]
	v_lshlrev_b32_e32 v232, 16, v152
	v_and_b32_e32 v233, 0xffff0000, v152
	v_pk_mul_f32 v[66:67], v[66:67], v[232:233]
	v_lshlrev_b32_e32 v232, 16, v153
	v_and_b32_e32 v233, 0xffff0000, v153
	v_pk_mul_f32 v[68:69], v[68:69], v[232:233]
	s_cmp_lg_u64 s[36:37], 0
	s_cbranch_scc0 .Lmx_m1_s3
	v_lshlrev_b32_e32 v232, 16, v166
	v_and_b32_e32 v233, 0xffff0000, v166
	v_pk_add_f32 v[248:249], v[248:249], v[232:233]
	v_lshlrev_b32_e32 v232, 16, v167
	v_and_b32_e32 v233, 0xffff0000, v167
	v_pk_add_f32 v[250:251], v[250:251], v[232:233]
	v_lshlrev_b32_e32 v232, 16, v168
	v_and_b32_e32 v233, 0xffff0000, v168
	v_pk_add_f32 v[66:67], v[66:67], v[232:233]
	v_lshlrev_b32_e32 v232, 16, v169
	v_and_b32_e32 v233, 0xffff0000, v169
	v_pk_add_f32 v[68:69], v[68:69], v[232:233]
.Lmx_m1_s3:
	v_cvt_pk_bf16_f32 v150, v248, v249
	v_cvt_pk_bf16_f32 v151, v250, v251
	v_cvt_pk_bf16_f32 v152, v66, v67
	v_cvt_pk_bf16_f32 v153, v68, v69
	global_store_dwordx4 v[70:71], v[150:153], off
; DI float bflo(unsigned v) { return __uint_as_float(v << 16); }
; DI float bfhi(unsigned v) { return __uint_as_float(v & 0xffff0000u); }
; DI void phase_mix(const Params& p, int l, unsigned char* smem) {
;     ...
;     for (int mi = 0; mi < 4; ++mi) {
;       if (mi > 0) __syncthreads();
;       stage_rm(acc[mi][0], acc[mi][1], stg, wm, wn, r, h);
;       __syncthreads();
; #pragma unroll 1
;       for (int q = 0; q < 4; ++q) {
;         const int cid = q * NTHR + tid, lr = cid >> 5, c8 = (cid & 31) * 8;
;         const float4 v0 = *(const float4*)(stg + lr * EP_LD + c8);
;         const float4 v1 = *(const float4*)(stg + lr * EP_LD + c8 + 4);
;         const int row = grow_of(m0, mi, lr), n = n0 + c8;
;         const uint4 g = *(const uint4*)(G + (size_t)row * 2048 + half * 1024 + n);
;         float4 o0 = make_float4(bflo(g.x) * v0.x, bfhi(g.x) * v0.y, bflo(g.y) * v0.z, bfhi(g.y) * v0.w);
;         float4 o1 = make_float4(bflo(g.z) * v1.x, bfhi(g.z) * v1.y, bflo(g.w) * v1.z, bfhi(g.w) * v1.w);
;         uint4* mp = (uint4*)(MIX + (size_t)row * 1024 + n);
;         if (half) {
;           const uint4 pr = *mp;
;           o0.x += bflo(pr.x); o0.y += bfhi(pr.x); o0.z += bflo(pr.y); o0.w += bfhi(pr.y);
;           o1.x += bflo(pr.z); o1.y += bfhi(pr.z); o1.z += bflo(pr.w); o1.w += bfhi(pr.w);
;         }
;         *mp = pack8f(o0, o1);
;       }
.LBB0_651:
	v_mov_b32_e32 v64, v32
	v_mov_b32_e32 v65, v48
	v_mov_b32_e32 v48, v33
	v_mov_b32_e32 v32, v34
	v_mov_b32_e32 v33, v50
	v_mov_b32_e32 v50, v35
	s_barrier
	ds_write2_b64 v97, v[32:33], v[50:51] offset0:8 offset1:140
	v_mov_b32_e32 v32, v36
	v_mov_b32_e32 v33, v52
	v_mov_b32_e32 v52, v37
	ds_write2_b64 v112, v[32:33], v[52:53] offset0:32 offset1:164
	v_mov_b32_e32 v32, v38
	v_mov_b32_e32 v33, v54
	v_mov_b32_e32 v54, v39
	ds_write2_b64 v113, v[32:33], v[54:55] offset0:40 offset1:172
	v_mov_b32_e32 v32, v40
	v_mov_b32_e32 v33, v56
	v_mov_b32_e32 v56, v41
	ds_write2_b64 v114, v[32:33], v[56:57] offset0:64 offset1:196
	v_mov_b32_e32 v32, v42
	v_mov_b32_e32 v33, v58
	v_mov_b32_e32 v58, v43
	ds_write2_b64 v115, v[32:33], v[58:59] offset0:72 offset1:204
	v_mov_b32_e32 v32, v44
	v_mov_b32_e32 v33, v60
	v_mov_b32_e32 v60, v45
	ds_write2_b64 v116, v[32:33], v[60:61] offset0:96 offset1:228
	v_mov_b32_e32 v32, v46
	v_mov_b32_e32 v33, v62
	v_mov_b32_e32 v62, v47
	v_add_u32_e32 v42, 64, v129
	s_mov_b32 s16, 0
	ds_write2_b64 v130, v[64:65], v[48:49] offset1:132
	ds_write2_b64 v117, v[32:33], v[62:63] offset0:104 offset1:236
	s_waitcnt lgkmcnt(0)
	s_barrier
	v_lshrrev_b32_e32 v137, 5, v128
	v_mad_u32_u24 v216, v137, s85, v96
	v_add_u32_e32 v137, v137, v42
	s_mov_b32 s38, 0x10000
	s_mov_b32 s39, 0
	s_mov_b32 s40, 0x70000
	s_mov_b32 s41, 0
	s_mov_b32 s42, 0x8000
	s_mov_b32 s43, 0
	s_mov_b32 s44, 0x38000
	s_mov_b32 s45, 0
	v_lshlrev_b32_e32 v32, 12, v137
	v_mov_b32_e32 v33, 0
	v_lshlrev_b32_e32 v38, 11, v137
	v_mov_b32_e32 v39, 0
	v_lshl_add_u64 v[32:33], v[32:33], 0, v[98:99]
	v_lshl_add_u64 v[38:39], v[38:39], 0, v[100:101]
	global_load_dwordx4 v[138:141], v[32:33], off
	v_lshl_add_u64 v[32:33], v[32:33], 0, s[38:39]
	global_load_dwordx4 v[142:145], v[32:33], off
	v_lshl_add_u64 v[32:33], v[32:33], 0, s[40:41]
	global_load_dwordx4 v[146:149], v[32:33], off
	v_lshl_add_u64 v[32:33], v[32:33], 0, s[38:39]
	global_load_dwordx4 v[150:153], v[32:33], off
	s_cmp_lg_u64 s[36:37], 0
	s_cbranch_scc0 .Lmx_m2_np
	v_mov_b32_e32 v32, v38
	v_mov_b32_e32 v33, v39
	global_load_dwordx4 v[154:157], v[32:33], off
	v_lshl_add_u64 v[32:33], v[32:33], 0, s[42:43]
	global_load_dwordx4 v[158:161], v[32:33], off
	v_lshl_add_u64 v[32:33], v[32:33], 0, s[44:45]
	global_load_dwordx4 v[162:165], v[32:33], off
	v_lshl_add_u64 v[32:33], v[32:33], 0, s[42:43]
	global_load_dwordx4 v[166:169], v[32:33], off
.Lmx_m2_np:
	ds_read_b128 v[170:173], v216
	ds_read_b128 v[244:247], v216 offset:16
	ds_read_b128 v[248:251], v216 offset:16896
	ds_read_b128 v[34:37], v216 offset:16912
	s_waitcnt vmcnt(3)
	s_waitcnt lgkmcnt(2)
	v_lshlrev_b32_e32 v232, 16, v138
	v_and_b32_e32 v233, 0xffff0000, v138
	v_pk_mul_f32 v[170:171], v[170:171], v[232:233]
	v_lshlrev_b32_e32 v232, 16, v139
	v_and_b32_e32 v233, 0xffff0000, v139
	v_pk_mul_f32 v[172:173], v[172:173], v[232:233]
	v_lshlrev_b32_e32 v232, 16, v140
	v_and_b32_e32 v233, 0xffff0000, v140
	v_pk_mul_f32 v[244:245], v[244:245], v[232:233]
	v_lshlrev_b32_e32 v232, 16, v141
	v_and_b32_e32 v233, 0xffff0000, v141
	v_pk_mul_f32 v[246:247], v[246:247], v[232:233]
	s_cmp_lg_u64 s[36:37], 0
	s_cbranch_scc0 .Lmx_m2_s0
	v_lshlrev_b32_e32 v232, 16, v154
	v_and_b32_e32 v233, 0xffff0000, v154
	v_pk_add_f32 v[170:171], v[170:171], v[232:233]
	v_lshlrev_b32_e32 v232, 16, v155
	v_and_b32_e32 v233, 0xffff0000, v155
	v_pk_add_f32 v[172:173], v[172:173], v[232:233]
	v_lshlrev_b32_e32 v232, 16, v156
	v_and_b32_e32 v233, 0xffff0000, v156
	v_pk_add_f32 v[244:245], v[244:245], v[232:233]
	v_lshlrev_b32_e32 v232, 16, v157
	v_and_b32_e32 v233, 0xffff0000, v157
	v_pk_add_f32 v[246:247], v[246:247], v[232:233]
.Lmx_m2_s0:
	v_cvt_pk_bf16_f32 v138, v170, v171
	v_cvt_pk_bf16_f32 v139, v172, v173
	v_cvt_pk_bf16_f32 v140, v244, v245
	v_cvt_pk_bf16_f32 v141, v246, v247
	global_store_dwordx4 v[38:39], v[138:141], off
	v_lshl_add_u64 v[38:39], v[38:39], 0, s[42:43]
	ds_read_b128 v[170:173], v216 offset:33792
	ds_read_b128 v[244:247], v216 offset:33808
	s_waitcnt vmcnt(3)
	s_waitcnt lgkmcnt(2)
	v_lshlrev_b32_e32 v232, 16, v142
	v_and_b32_e32 v233, 0xffff0000, v142
	v_pk_mul_f32 v[248:249], v[248:249], v[232:233]
	v_lshlrev_b32_e32 v232, 16, v143
	v_and_b32_e32 v233, 0xffff0000, v143
	v_pk_mul_f32 v[250:251], v[250:251], v[232:233]
	v_lshlrev_b32_e32 v232, 16, v144
	v_and_b32_e32 v233, 0xffff0000, v144
	v_pk_mul_f32 v[34:35], v[34:35], v[232:233]
	v_lshlrev_b32_e32 v232, 16, v145
	v_and_b32_e32 v233, 0xffff0000, v145
	v_pk_mul_f32 v[36:37], v[36:37], v[232:233]
	s_cmp_lg_u64 s[36:37], 0
	s_cbranch_scc0 .Lmx_m2_s1
	v_lshlrev_b32_e32 v232, 16, v158
	v_and_b32_e32 v233, 0xffff0000, v158
	v_pk_add_f32 v[248:249], v[248:249], v[232:233]
	v_lshlrev_b32_e32 v232, 16, v159
	v_and_b32_e32 v233, 0xffff0000, v159
	v_pk_add_f32 v[250:251], v[250:251], v[232:233]
	v_lshlrev_b32_e32 v232, 16, v160
	v_and_b32_e32 v233, 0xffff0000, v160
	v_pk_add_f32 v[34:35], v[34:35], v[232:233]
	v_lshlrev_b32_e32 v232, 16, v161
	v_and_b32_e32 v233, 0xffff0000, v161
	v_pk_add_f32 v[36:37], v[36:37], v[232:233]
; DI float bflo(unsigned v) { return __uint_as_float(v << 16); }
; DI float bfhi(unsigned v) { return __uint_as_float(v & 0xffff0000u); }
; DI void phase_mix(const Params& p, int l, unsigned char* smem) {
;     ...
;     for (int mi = 0; mi < 4; ++mi) {
;       if (mi > 0) __syncthreads();
;       stage_rm(acc[mi][0], acc[mi][1], stg, wm, wn, r, h);
;       __syncthreads();
; #pragma unroll 1
;       for (int q = 0; q < 4; ++q) {
;         const int cid = q * NTHR + tid, lr = cid >> 5, c8 = (cid & 31) * 8;
;         const float4 v0 = *(const float4*)(stg + lr * EP_LD + c8);
;         const float4 v1 = *(const float4*)(stg + lr * EP_LD + c8 + 4);
;         const int row = grow_of(m0, mi, lr), n = n0 + c8;
;         const uint4 g = *(const uint4*)(G + (size_t)row * 2048 + half * 1024 + n);
;         float4 o0 = make_float4(bflo(g.x) * v0.x, bfhi(g.x) * v0.y, bflo(g.y) * v0.z, bfhi(g.y) * v0.w);
;         float4 o1 = make_float4(bflo(g.z) * v1.x, bfhi(g.z) * v1.y, bflo(g.w) * v1.z, bfhi(g.w) * v1.w);
;         uint4* mp = (uint4*)(MIX + (size_t)row * 1024 + n);
;         if (half) {
;           const uint4 pr = *mp;
;           o0.x += bflo(pr.x); o0.y += bfhi(pr.x); o0.z += bflo(pr.y); o0.w += bfhi(pr.y);
;           o1.x += bflo(pr.z); o1.y += bfhi(pr.z); o1.z += bflo(pr.w); o1.w += bfhi(pr.w);
;         }
;         *mp = pack8f(o0, o1);
;       }
.Lmx_m2_s1:
	v_cvt_pk_bf16_f32 v142, v248, v249
	v_cvt_pk_bf16_f32 v143, v250, v251
	v_cvt_pk_bf16_f32 v144, v34, v35
	v_cvt_pk_bf16_f32 v145, v36, v37
	global_store_dwordx4 v[38:39], v[142:145], off
	v_lshl_add_u64 v[38:39], v[38:39], 0, s[44:45]
	ds_read_b128 v[248:251], v216 offset:50688
	ds_read_b128 v[34:37], v216 offset:50704
	s_waitcnt vmcnt(3)
	s_waitcnt lgkmcnt(2)
	v_lshlrev_b32_e32 v232, 16, v146
	v_and_b32_e32 v233, 0xffff0000, v146
	v_pk_mul_f32 v[170:171], v[170:171], v[232:233]
	v_lshlrev_b32_e32 v232, 16, v147
	v_and_b32_e32 v233, 0xffff0000, v147
	v_pk_mul_f32 v[172:173], v[172:173], v[232:233]
	v_lshlrev_b32_e32 v232, 16, v148
	v_and_b32_e32 v233, 0xffff0000, v148
	v_pk_mul_f32 v[244:245], v[244:245], v[232:233]
	v_lshlrev_b32_e32 v232, 16, v149
	v_and_b32_e32 v233, 0xffff0000, v149
	v_pk_mul_f32 v[246:247], v[246:247], v[232:233]
	s_cmp_lg_u64 s[36:37], 0
	s_cbranch_scc0 .Lmx_m2_s2
	v_lshlrev_b32_e32 v232, 16, v162
	v_and_b32_e32 v233, 0xffff0000, v162
	v_pk_add_f32 v[170:171], v[170:171], v[232:233]
	v_lshlrev_b32_e32 v232, 16, v163
	v_and_b32_e32 v233, 0xffff0000, v163
	v_pk_add_f32 v[172:173], v[172:173], v[232:233]
	v_lshlrev_b32_e32 v232, 16, v164
	v_and_b32_e32 v233, 0xffff0000, v164
	v_pk_add_f32 v[244:245], v[244:245], v[232:233]
	v_lshlrev_b32_e32 v232, 16, v165
	v_and_b32_e32 v233, 0xffff0000, v165
	v_pk_add_f32 v[246:247], v[246:247], v[232:233]
.Lmx_m2_s2:
	v_cvt_pk_bf16_f32 v146, v170, v171
	v_cvt_pk_bf16_f32 v147, v172, v173
	v_cvt_pk_bf16_f32 v148, v244, v245
	v_cvt_pk_bf16_f32 v149, v246, v247
	global_store_dwordx4 v[38:39], v[146:149], off
	v_lshl_add_u64 v[38:39], v[38:39], 0, s[42:43]
	s_waitcnt vmcnt(3)
	s_waitcnt lgkmcnt(0)
	v_lshlrev_b32_e32 v232, 16, v150
	v_and_b32_e32 v233, 0xffff0000, v150
	v_pk_mul_f32 v[248:249], v[248:249], v[232:233]
	v_lshlrev_b32_e32 v232, 16, v151
	v_and_b32_e32 v233, 0xffff0000, v151
	v_pk_mul_f32 v[250:251], v[250:251], v[232:233]
	v_lshlrev_b32_e32 v232, 16, v152
	v_and_b32_e32 v233, 0xffff0000, v152
	v_pk_mul_f32 v[34:35], v[34:35], v[232:233]
	v_lshlrev_b32_e32 v232, 16, v153
	v_and_b32_e32 v233, 0xffff0000, v153
	v_pk_mul_f32 v[36:37], v[36:37], v[232:233]
	s_cmp_lg_u64 s[36:37], 0
	s_cbranch_scc0 .Lmx_m2_s3
	v_lshlrev_b32_e32 v232, 16, v166
	v_and_b32_e32 v233, 0xffff0000, v166
	v_pk_add_f32 v[248:249], v[248:249], v[232:233]
	v_lshlrev_b32_e32 v232, 16, v167
	v_and_b32_e32 v233, 0xffff0000, v167
	v_pk_add_f32 v[250:251], v[250:251], v[232:233]
	v_lshlrev_b32_e32 v232, 16, v168
	v_and_b32_e32 v233, 0xffff0000, v168
	v_pk_add_f32 v[34:35], v[34:35], v[232:233]
	v_lshlrev_b32_e32 v232, 16, v169
	v_and_b32_e32 v233, 0xffff0000, v169
	v_pk_add_f32 v[36:37], v[36:37], v[232:233]
.Lmx_m2_s3:
	v_cvt_pk_bf16_f32 v150, v248, v249
	v_cvt_pk_bf16_f32 v151, v250, v251
	v_cvt_pk_bf16_f32 v152, v34, v35
	v_cvt_pk_bf16_f32 v153, v36, v37
	global_store_dwordx4 v[38:39], v[150:153], off
.LBB0_655:
	v_mov_b32_e32 v32, v0
	v_mov_b32_e32 v33, v16
	v_mov_b32_e32 v16, v1
	v_mov_b32_e32 v0, v2
	v_mov_b32_e32 v1, v18
	v_mov_b32_e32 v18, v3
	s_barrier
	ds_write2_b64 v97, v[0:1], v[18:19] offset0:8 offset1:140
	v_mov_b32_e32 v0, v4
	v_mov_b32_e32 v1, v20
	v_mov_b32_e32 v20, v5
	ds_write2_b64 v112, v[0:1], v[20:21] offset0:32 offset1:164
	v_mov_b32_e32 v0, v6
	v_mov_b32_e32 v1, v22
	v_mov_b32_e32 v22, v7
	ds_write2_b64 v113, v[0:1], v[22:23] offset0:40 offset1:172
	v_mov_b32_e32 v0, v8
	v_mov_b32_e32 v1, v24
	v_mov_b32_e32 v24, v9
	ds_write2_b64 v114, v[0:1], v[24:25] offset0:64 offset1:196
	v_mov_b32_e32 v0, v10
	v_mov_b32_e32 v1, v26
	v_mov_b32_e32 v26, v11
	ds_write2_b64 v115, v[0:1], v[26:27] offset0:72 offset1:204
	v_mov_b32_e32 v0, v12
	v_mov_b32_e32 v1, v28
	v_mov_b32_e32 v28, v13
	ds_write2_b64 v116, v[0:1], v[28:29] offset0:96 offset1:228
	v_mov_b32_e32 v0, v14
	v_mov_b32_e32 v1, v30
	v_mov_b32_e32 v30, v15
	v_add_u32_e32 v10, 0x60, v129
	s_mov_b32 s16, 0
	ds_write2_b64 v130, v[32:33], v[16:17] offset1:132
	ds_write2_b64 v117, v[0:1], v[30:31] offset0:104 offset1:236
	s_waitcnt lgkmcnt(0)
	s_barrier
	v_lshrrev_b32_e32 v137, 5, v128
	v_mad_u32_u24 v216, v137, s85, v96
	v_add_u32_e32 v137, v137, v10
	s_mov_b32 s38, 0x10000
	s_mov_b32 s39, 0
	s_mov_b32 s40, 0x70000
	s_mov_b32 s41, 0
	s_mov_b32 s42, 0x8000
	s_mov_b32 s43, 0
	s_mov_b32 s44, 0x38000
	s_mov_b32 s45, 0
	v_lshlrev_b32_e32 v0, 12, v137
	v_mov_b32_e32 v1, 0
	v_lshlrev_b32_e32 v6, 11, v137
	v_mov_b32_e32 v7, 0
	v_lshl_add_u64 v[0:1], v[0:1], 0, v[98:99]
	v_lshl_add_u64 v[6:7], v[6:7], 0, v[100:101]
	global_load_dwordx4 v[138:141], v[0:1], off
	v_lshl_add_u64 v[0:1], v[0:1], 0, s[38:39]
	global_load_dwordx4 v[142:145], v[0:1], off
	v_lshl_add_u64 v[0:1], v[0:1], 0, s[40:41]
	global_load_dwordx4 v[146:149], v[0:1], off
	v_lshl_add_u64 v[0:1], v[0:1], 0, s[38:39]
	global_load_dwordx4 v[150:153], v[0:1], off
	s_cmp_lg_u64 s[36:37], 0
	s_cbranch_scc0 .Lmx_m3_np
	v_mov_b32_e32 v0, v6
	v_mov_b32_e32 v1, v7
	global_load_dwordx4 v[154:157], v[0:1], off
	v_lshl_add_u64 v[0:1], v[0:1], 0, s[42:43]
	global_load_dwordx4 v[158:161], v[0:1], off
	v_lshl_add_u64 v[0:1], v[0:1], 0, s[44:45]
	global_load_dwordx4 v[162:165], v[0:1], off
	v_lshl_add_u64 v[0:1], v[0:1], 0, s[42:43]
	global_load_dwordx4 v[166:169], v[0:1], off
; DI float bflo(unsigned v) { return __uint_as_float(v << 16); }
; DI float bfhi(unsigned v) { return __uint_as_float(v & 0xffff0000u); }
; DI void phase_mix(const Params& p, int l, unsigned char* smem) {
;     ...
; #pragma unroll 1
;       for (int q = 0; q < 4; ++q) {
;         const int cid = q * NTHR + tid, lr = cid >> 5, c8 = (cid & 31) * 8;
;         const float4 v0 = *(const float4*)(stg + lr * EP_LD + c8);
;         const float4 v1 = *(const float4*)(stg + lr * EP_LD + c8 + 4);
;         const int row = grow_of(m0, mi, lr), n = n0 + c8;
;         const uint4 g = *(const uint4*)(G + (size_t)row * 2048 + half * 1024 + n);
;         float4 o0 = make_float4(bflo(g.x) * v0.x, bfhi(g.x) * v0.y, bflo(g.y) * v0.z, bfhi(g.y) * v0.w);
;         float4 o1 = make_float4(bflo(g.z) * v1.x, bfhi(g.z) * v1.y, bflo(g.w) * v1.z, bfhi(g.w) * v1.w);
;         uint4* mp = (uint4*)(MIX + (size_t)row * 1024 + n);
;         if (half) {
;           const uint4 pr = *mp;
;           o0.x += bflo(pr.x); o0.y += bfhi(pr.x); o0.z += bflo(pr.y); o0.w += bfhi(pr.y);
;           o1.x += bflo(pr.z); o1.y += bfhi(pr.z); o1.z += bflo(pr.w); o1.w += bfhi(pr.w);
;         }
;         *mp = pack8f(o0, o1);
;       }
.Lmx_m3_np:
	ds_read_b128 v[170:173], v216
	ds_read_b128 v[244:247], v216 offset:16
	ds_read_b128 v[248:251], v216 offset:16896
	ds_read_b128 v[2:5], v216 offset:16912
	s_waitcnt vmcnt(3)
	s_waitcnt lgkmcnt(2)
	v_lshlrev_b32_e32 v232, 16, v138
	v_and_b32_e32 v233, 0xffff0000, v138
	v_pk_mul_f32 v[170:171], v[170:171], v[232:233]
	v_lshlrev_b32_e32 v232, 16, v139
	v_and_b32_e32 v233, 0xffff0000, v139
	v_pk_mul_f32 v[172:173], v[172:173], v[232:233]
	v_lshlrev_b32_e32 v232, 16, v140
	v_and_b32_e32 v233, 0xffff0000, v140
	v_pk_mul_f32 v[244:245], v[244:245], v[232:233]
	v_lshlrev_b32_e32 v232, 16, v141
	v_and_b32_e32 v233, 0xffff0000, v141
	v_pk_mul_f32 v[246:247], v[246:247], v[232:233]
	s_cmp_lg_u64 s[36:37], 0
	s_cbranch_scc0 .Lmx_m3_s0
	v_lshlrev_b32_e32 v232, 16, v154
	v_and_b32_e32 v233, 0xffff0000, v154
	v_pk_add_f32 v[170:171], v[170:171], v[232:233]
	v_lshlrev_b32_e32 v232, 16, v155
	v_and_b32_e32 v233, 0xffff0000, v155
	v_pk_add_f32 v[172:173], v[172:173], v[232:233]
	v_lshlrev_b32_e32 v232, 16, v156
	v_and_b32_e32 v233, 0xffff0000, v156
	v_pk_add_f32 v[244:245], v[244:245], v[232:233]
	v_lshlrev_b32_e32 v232, 16, v157
	v_and_b32_e32 v233, 0xffff0000, v157
	v_pk_add_f32 v[246:247], v[246:247], v[232:233]
.Lmx_m3_s0:
	v_cvt_pk_bf16_f32 v138, v170, v171
	v_cvt_pk_bf16_f32 v139, v172, v173
	v_cvt_pk_bf16_f32 v140, v244, v245
	v_cvt_pk_bf16_f32 v141, v246, v247
	global_store_dwordx4 v[6:7], v[138:141], off
	v_lshl_add_u64 v[6:7], v[6:7], 0, s[42:43]
	ds_read_b128 v[170:173], v216 offset:33792
	ds_read_b128 v[244:247], v216 offset:33808
	s_waitcnt vmcnt(3)
	s_waitcnt lgkmcnt(2)
	v_lshlrev_b32_e32 v232, 16, v142
	v_and_b32_e32 v233, 0xffff0000, v142
	v_pk_mul_f32 v[248:249], v[248:249], v[232:233]
	v_lshlrev_b32_e32 v232, 16, v143
	v_and_b32_e32 v233, 0xffff0000, v143
	v_pk_mul_f32 v[250:251], v[250:251], v[232:233]
	v_lshlrev_b32_e32 v232, 16, v144
	v_and_b32_e32 v233, 0xffff0000, v144
	v_pk_mul_f32 v[2:3], v[2:3], v[232:233]
	v_lshlrev_b32_e32 v232, 16, v145
	v_and_b32_e32 v233, 0xffff0000, v145
	v_pk_mul_f32 v[4:5], v[4:5], v[232:233]
	s_cmp_lg_u64 s[36:37], 0
	s_cbranch_scc0 .Lmx_m3_s1
	v_lshlrev_b32_e32 v232, 16, v158
	v_and_b32_e32 v233, 0xffff0000, v158
	v_pk_add_f32 v[248:249], v[248:249], v[232:233]
	v_lshlrev_b32_e32 v232, 16, v159
	v_and_b32_e32 v233, 0xffff0000, v159
	v_pk_add_f32 v[250:251], v[250:251], v[232:233]
	v_lshlrev_b32_e32 v232, 16, v160
	v_and_b32_e32 v233, 0xffff0000, v160
	v_pk_add_f32 v[2:3], v[2:3], v[232:233]
	v_lshlrev_b32_e32 v232, 16, v161
	v_and_b32_e32 v233, 0xffff0000, v161
	v_pk_add_f32 v[4:5], v[4:5], v[232:233]
.Lmx_m3_s1:
	v_cvt_pk_bf16_f32 v142, v248, v249
	v_cvt_pk_bf16_f32 v143, v250, v251
	v_cvt_pk_bf16_f32 v144, v2, v3
	v_cvt_pk_bf16_f32 v145, v4, v5
	global_store_dwordx4 v[6:7], v[142:145], off
	v_lshl_add_u64 v[6:7], v[6:7], 0, s[44:45]
	ds_read_b128 v[248:251], v216 offset:50688
	ds_read_b128 v[2:5], v216 offset:50704
	s_waitcnt vmcnt(3)
	s_waitcnt lgkmcnt(2)
	v_lshlrev_b32_e32 v232, 16, v146
	v_and_b32_e32 v233, 0xffff0000, v146
	v_pk_mul_f32 v[170:171], v[170:171], v[232:233]
	v_lshlrev_b32_e32 v232, 16, v147
	v_and_b32_e32 v233, 0xffff0000, v147
	v_pk_mul_f32 v[172:173], v[172:173], v[232:233]
	v_lshlrev_b32_e32 v232, 16, v148
	v_and_b32_e32 v233, 0xffff0000, v148
	v_pk_mul_f32 v[244:245], v[244:245], v[232:233]
	v_lshlrev_b32_e32 v232, 16, v149
	v_and_b32_e32 v233, 0xffff0000, v149
	v_pk_mul_f32 v[246:247], v[246:247], v[232:233]
	s_cmp_lg_u64 s[36:37], 0
	s_cbranch_scc0 .Lmx_m3_s2
	v_lshlrev_b32_e32 v232, 16, v162
	v_and_b32_e32 v233, 0xffff0000, v162
	v_pk_add_f32 v[170:171], v[170:171], v[232:233]
	v_lshlrev_b32_e32 v232, 16, v163
	v_and_b32_e32 v233, 0xffff0000, v163
	v_pk_add_f32 v[172:173], v[172:173], v[232:233]
	v_lshlrev_b32_e32 v232, 16, v164
	v_and_b32_e32 v233, 0xffff0000, v164
	v_pk_add_f32 v[244:245], v[244:245], v[232:233]
	v_lshlrev_b32_e32 v232, 16, v165
	v_and_b32_e32 v233, 0xffff0000, v165
	v_pk_add_f32 v[246:247], v[246:247], v[232:233]
.Lmx_m3_s2:
	v_cvt_pk_bf16_f32 v146, v170, v171
	v_cvt_pk_bf16_f32 v147, v172, v173
	v_cvt_pk_bf16_f32 v148, v244, v245
	v_cvt_pk_bf16_f32 v149, v246, v247
	global_store_dwordx4 v[6:7], v[146:149], off
	v_lshl_add_u64 v[6:7], v[6:7], 0, s[42:43]
	s_waitcnt vmcnt(3)
	s_waitcnt lgkmcnt(0)
	v_lshlrev_b32_e32 v232, 16, v150
	v_and_b32_e32 v233, 0xffff0000, v150
	v_pk_mul_f32 v[248:249], v[248:249], v[232:233]
	v_lshlrev_b32_e32 v232, 16, v151
	v_and_b32_e32 v233, 0xffff0000, v151
	v_pk_mul_f32 v[250:251], v[250:251], v[232:233]
	v_lshlrev_b32_e32 v232, 16, v152
	v_and_b32_e32 v233, 0xffff0000, v152
	v_pk_mul_f32 v[2:3], v[2:3], v[232:233]
	v_lshlrev_b32_e32 v232, 16, v153
	v_and_b32_e32 v233, 0xffff0000, v153
	v_pk_mul_f32 v[4:5], v[4:5], v[232:233]
	s_cmp_lg_u64 s[36:37], 0
	s_cbranch_scc0 .Lmx_m3_s3
	v_lshlrev_b32_e32 v232, 16, v166
	v_and_b32_e32 v233, 0xffff0000, v166
	v_pk_add_f32 v[248:249], v[248:249], v[232:233]
	v_lshlrev_b32_e32 v232, 16, v167
	v_and_b32_e32 v233, 0xffff0000, v167
	v_pk_add_f32 v[250:251], v[250:251], v[232:233]
	v_lshlrev_b32_e32 v232, 16, v168
	v_and_b32_e32 v233, 0xffff0000, v168
	v_pk_add_f32 v[2:3], v[2:3], v[232:233]
	v_lshlrev_b32_e32 v232, 16, v169
	v_and_b32_e32 v233, 0xffff0000, v169
	v_pk_add_f32 v[4:5], v[4:5], v[232:233]
.Lmx_m3_s3:
	v_cvt_pk_bf16_f32 v150, v248, v249
	v_cvt_pk_bf16_f32 v151, v250, v251
	v_cvt_pk_bf16_f32 v152, v2, v3
	v_cvt_pk_bf16_f32 v153, v4, v5
	global_store_dwordx4 v[6:7], v[150:153], off
	s_branch .LBB0_610

; DI int otid() { int t = threadIdx.x; asm volatile("" : "+v"(t)); return t; }
; DI void gbar(unsigned* ctl, unsigned& k) {
;   __syncthreads();
;   ++k;
;   if (otid() == 0) {
;     __threadfence();
;     const unsigned x = blockIdx.x & 7;
;     const unsigned gsz = (gridDim.x + 7 - x) >> 3;
;     const unsigned ngroups = gridDim.x < 8 ? gridDim.x : 8;
;     unsigned* gc = ctl + 64 + x * 32;
;     unsigned* gl = ctl + 32;
;     const unsigned old = __hip_atomic_fetch_add(gc, 1u, __ATOMIC_RELAXED, __HIP_MEMORY_SCOPE_AGENT);
;     if (old + 1 == k * gsz) {
;       __threadfence();
;       __hip_atomic_fetch_add(gl, 1u, __ATOMIC_RELAXED, __HIP_MEMORY_SCOPE_AGENT);
;     }
.LBB0_662:
	v_mov_b32_e32 v0, v212
	s_barrier
	s_barrier
	s_nop 0
	v_cmp_eq_u32_e32 vcc, 0, v0
	s_and_saveexec_b64 s[2:3], vcc
	s_cbranch_execz .LBB0_670
	buffer_wbl2 sc1
	s_waitcnt vmcnt(0)
	buffer_inv sc1
	global_atomic_add v0, v[176:177], v221, off sc0
	v_readlane_b32 s4, v254, 1
	s_add_i32 s8, s4, 3
	v_mul_lo_u32 v1, s8, v213
	s_waitcnt vmcnt(0)
	v_add_u32_e32 v0, 1, v0
	v_cmp_eq_u32_e32 vcc, v0, v1
	s_and_saveexec_b64 s[4:5], vcc
	s_cbranch_execz .LBB0_666
	s_mov_b64 s[6:7], exec
	v_mbcnt_lo_u32_b32 v0, s6, 0
	v_mbcnt_hi_u32_b32 v0, s7, v0
	v_cmp_eq_u32_e32 vcc, 0, v0
	s_and_b64 s[10:11], exec, vcc
	s_mov_b64 exec, s[10:11]
	s_cbranch_execz .LBB0_666
	s_bcnt1_i32_b64 s6, s[6:7]
	v_mov_b32_e32 v0, s6
	v_readlane_b32 s6, v253, 10
	v_readlane_b32 s7, v253, 11
	s_nop 4
	global_atomic_add v179, v0, s[6:7]

; DI int otid() { int t = threadIdx.x; asm volatile("" : "+v"(t)); return t; }
; template <class PF, class EF>
; DI void gemm_stream(int lda, int ldw, int K, unsigned char* smem, PF ptrs, EF epi) {
;   const int tid = otid(), lane = tid & 63, w = tid >> 6;
;   const int wm = w >> 2, wn = w & 3, r = lane & 31, h = lane >> 5;
;   unsigned char* sbase = smem + GS_BASE;
;   constexpr int SLOT = 512 * 64;
;   const int nh = K >> 5;
;   const int c0 = (h ^ ((r >> 2) & 3)) * 16, c1 = c0 ^ 32;
;   const int aoff = (wm * 128 + r) * 64, boff = (256 + wn * 64 + r) * 64;
;   const int lr16 = lane >> 2, lchunk = (lane & 3) ^ ((lane >> 4) & 3);
;   const int wu = __builtin_amdgcn_readfirstlane(w);
;   const bool isB = wu >= 4;
;   const unsigned goff = isB ? (unsigned)((((wu - 4) * 64 + 2 * lr16) * ldw + lchunk * 8) * 2)
;                             : (unsigned)(((wu * 64 + lr16) * lda + lchunk * 8) * 2);
; DI void gbar(unsigned* ctl, unsigned& k) {
;     ...
;     while (__hip_atomic_load(gl, __ATOMIC_RELAXED, __HIP_MEMORY_SCOPE_AGENT) < k * ngroups) __builtin_amdgcn_s_sleep(1);
;     __threadfence();
;   }
;   __syncthreads();
.LBB0_668:
	s_sleep 1
	global_load_dword v1, v179, s[6:7] sc1
	s_waitcnt vmcnt(0)
	v_cmp_ge_u32_e32 vcc, v1, v0
	s_or_b64 s[4:5], vcc, s[4:5]
	s_andn2_b64 exec, exec, s[4:5]
	s_cbranch_execnz .LBB0_668
.LBB0_669:
	buffer_inv sc1
.LBB0_670:
	s_or_b64 exec, exec, s[2:3]
	v_mov_b32_e32 v0, v212
	s_barrier
	s_nop 0
	v_mov_b32_e32 v0, v212
	s_nop 0
	v_readfirstlane_b32 s4, v0
	s_ashr_i32 s6, s4, 6
	s_cmp_gt_i32 s6, 3
	v_lshrrev_b32_e32 v2, 4, v0
	s_cselect_b64 s[2:3], -1, 0
	s_and_b32 s7, s4, 0x7fffffc0
	v_bfe_u32 v1, v0, 2, 4
	v_bitop3_b32 v2, v2, 3, v0 bitop3:0x48
	s_cmp_lt_i32 s6, 4
	s_mov_b64 s[4:5], -1
	s_cbranch_scc0 .LBB0_672
	v_or_b32_e32 v3, s7, v1
	v_lshlrev_b32_e32 v3, 11, v3
	v_lshl_or_b32 v182, v2, 4, v3
	s_mov_b64 s[4:5], 0

; DI int otid() { int t = threadIdx.x; asm volatile("" : "+v"(t)); return t; }
; DI void gbar(unsigned* ctl, unsigned& k) {
;   __syncthreads();
;   ++k;
;   if (otid() == 0) {
;     __threadfence();
;     const unsigned x = blockIdx.x & 7;
;     const unsigned gsz = (gridDim.x + 7 - x) >> 3;
;     const unsigned ngroups = gridDim.x < 8 ? gridDim.x : 8;
;     unsigned* gc = ctl + 64 + x * 32;
;     unsigned* gl = ctl + 32;
;     const unsigned old = __hip_atomic_fetch_add(gc, 1u, __ATOMIC_RELAXED, __HIP_MEMORY_SCOPE_AGENT);
;     if (old + 1 == k * gsz) {
;       __threadfence();
;       __hip_atomic_fetch_add(gl, 1u, __ATOMIC_RELAXED, __HIP_MEMORY_SCOPE_AGENT);
;     }
.LBB0_758:
	v_mov_b32_e32 v0, v212
	s_barrier
	s_barrier
	s_nop 0
	v_cmp_eq_u32_e32 vcc, 0, v0
	s_and_saveexec_b64 s[2:3], vcc
	s_cbranch_execz .LBB0_766
	buffer_wbl2 sc1
	s_waitcnt vmcnt(0)
	buffer_inv sc1
	global_atomic_add v0, v[176:177], v221, off sc0
	v_readlane_b32 s4, v254, 1
	s_add_i32 s8, s4, 4
	v_mul_lo_u32 v1, s8, v213
	s_waitcnt vmcnt(0)
	v_add_u32_e32 v0, 1, v0
	v_cmp_eq_u32_e32 vcc, v0, v1
	s_and_saveexec_b64 s[4:5], vcc
	s_cbranch_execz .LBB0_762
	s_mov_b64 s[6:7], exec
	v_mbcnt_lo_u32_b32 v0, s6, 0
	v_mbcnt_hi_u32_b32 v0, s7, v0
	v_cmp_eq_u32_e32 vcc, 0, v0
	s_and_b64 s[10:11], exec, vcc
	s_mov_b64 exec, s[10:11]
	s_cbranch_execz .LBB0_762
	s_bcnt1_i32_b64 s6, s[6:7]
	v_mov_b32_e32 v0, s6
	v_readlane_b32 s6, v253, 10
	v_readlane_b32 s7, v253, 11
	s_nop 4
	global_atomic_add v179, v0, s[6:7]

; DI void ln_pass(const Params& p, int mode, int l, unsigned char* smem) {
;     ...
;   float lg[16], lb[16];
;   if (first) {
; #pragma unroll
;     for (int i = 0; i < 4; ++i) {
;       const float4 g = *(const float4*)(lng + i * 256 + lane * 4);
;       const float4 b = *(const float4*)(lnb + i * 256 + lane * 4);
;       lg[i * 4] = g.x; lg[i * 4 + 1] = g.y; lg[i * 4 + 2] = g.z; lg[i * 4 + 3] = g.w;
;       lb[i * 4] = b.x; lb[i * 4 + 1] = b.y; lb[i * 4 + 2] = b.z; lb[i * 4 + 3] = b.w;
;     }
;   }
;     ...
;   for (int chunk = blockIdx.x * 8 + w; chunk < TOKP / 32; chunk += gridDim.x * 8) {
;     const int row0 = chunk * 32;
;     float msh[16], msc[16];
;     if (second) load_mod(row0, msh, msc);
;     const float* src0 = (mode == 0) ? p.in[0] + (size_t)row0 * 1024 : p.out + (size_t)row0 * 1024;
;     float4 nx0 = *(const float4*)(src0 + lane * 4), nx1 = *(const float4*)(src0 + 256 + lane * 4);
;     float4 nx2 = *(const float4*)(src0 + 512 + lane * 4), nx3 = *(const float4*)(src0 + 768 + lane * 4);
.LBB0_764:
	s_sleep 1
	global_load_dword v1, v179, s[6:7] sc1
	s_waitcnt vmcnt(0)
	v_cmp_ge_u32_e32 vcc, v1, v0
	s_or_b64 s[4:5], vcc, s[4:5]
	s_andn2_b64 exec, exec, s[4:5]
	s_cbranch_execnz .LBB0_764
.LBB0_765:
	buffer_inv sc1
.LBB0_766:
	s_or_b64 exec, exec, s[2:3]
	v_readlane_b32 s2, v254, 21
	v_readlane_b32 s3, v254, 22
	v_readlane_b32 s16, v253, 43
	s_mov_b32 s3, s83
	v_readlane_b32 s17, v253, 44
	s_lshl_b64 s[12:13], s[2:3], 2
	v_readlane_b32 s18, v253, 45
	v_readlane_b32 s19, v253, 46
	s_mov_b64 s[8:9], s[16:17]
	v_mov_b32_e32 v108, v212
	s_mov_b64 s[10:11], s[18:19]
	s_add_u32 s16, s8, s12
	s_barrier
	s_addc_u32 s17, s9, s13
	v_and_b32_e32 v109, 63, v108
	s_add_u32 s18, s10, s12
	v_lshlrev_b32_e32 v28, 4, v109
	s_addc_u32 s19, s11, s13
	s_barrier
	global_load_dwordx4 v[0:3], v28, s[16:17]
	global_load_dwordx4 v[4:7], v28, s[16:17] offset:1024
	global_load_dwordx4 v[8:11], v28, s[18:19]
	global_load_dwordx4 v[12:15], v28, s[18:19] offset:1024
	global_load_dwordx4 v[16:19], v28, s[16:17] offset:2048
	global_load_dwordx4 v[20:23], v28, s[16:17] offset:3072
	global_load_dwordx4 v[24:27], v28, s[18:19] offset:2048
	s_nop 0
	global_load_dwordx4 v[28:31], v28, s[18:19] offset:3072
	v_ashrrev_i32_e32 v32, 6, v108
	v_readlane_b32 s2, v252, 53
	v_readlane_b32 s20, v253, 47
	v_readlane_b32 s21, v253, 48
	v_add_u32_e32 v110, s2, v32
	s_movk_i32 s2, 0x800
	v_cmp_gt_i32_e32 vcc, s2, v110
	v_readlane_b32 s22, v253, 49
	v_readlane_b32 s23, v253, 50
	v_readlane_b32 s24, v253, 51
	v_readlane_b32 s25, v253, 52
	v_readlane_b32 s26, v253, 53
	v_readlane_b32 s27, v253, 54
	v_readlane_b32 s28, v253, 55
	v_readlane_b32 s29, v253, 56
	v_readlane_b32 s30, v253, 57
	v_readlane_b32 s31, v253, 58
	s_and_saveexec_b64 s[4:5], vcc
	v_readlane_b32 s20, v253, 31
	v_readlane_b32 s21, v253, 32
	s_cbranch_execz .LBB0_773
	v_lshlrev_b32_e32 v111, 2, v109
	v_readlane_b32 s2, v252, 51
	v_lshlrev_b32_e32 v178, 1, v111
	v_readlane_b32 s3, v252, 52
	s_mov_b32 s15, s83
	v_cmp_eq_u32_e32 vcc, 0, v109
	v_lshl_add_u64 v[80:81], s[2:3], 0, v[178:179]
	v_readlane_b32 s2, v253, 63
	s_mov_b64 s[6:7], 0
	s_waitcnt vmcnt(9)
	v_lshl_add_u32 v112, v32, 5, s2
	s_branch .LBB0_769

; DI int otid() { int t = threadIdx.x; asm volatile("" : "+v"(t)); return t; }
; DI void gbar(unsigned* ctl, unsigned& k) {
;   __syncthreads();
;   ++k;
;   if (otid() == 0) {
;     __threadfence();
;     const unsigned x = blockIdx.x & 7;
;     const unsigned gsz = (gridDim.x + 7 - x) >> 3;
;     const unsigned ngroups = gridDim.x < 8 ? gridDim.x : 8;
;     unsigned* gc = ctl + 64 + x * 32;
;     unsigned* gl = ctl + 32;
;     const unsigned old = __hip_atomic_fetch_add(gc, 1u, __ATOMIC_RELAXED, __HIP_MEMORY_SCOPE_AGENT);
;     if (old + 1 == k * gsz) {
;       __threadfence();
;       __hip_atomic_fetch_add(gl, 1u, __ATOMIC_RELAXED, __HIP_MEMORY_SCOPE_AGENT);
;     }
.LBB0_778:
	s_mov_b32 s60, 0x800000
	s_or_b64 exec, exec, s[4:5]
	s_waitcnt vmcnt(7)
	v_mov_b32_e32 v0, v212
	s_barrier
	s_nop 0
	v_cmp_eq_u32_e32 vcc, 0, v0
	s_and_saveexec_b64 s[2:3], vcc
	s_cbranch_execz .LBB0_786
	buffer_wbl2 sc1
	s_waitcnt vmcnt(0)
	buffer_inv sc1
	global_atomic_add v0, v[176:177], v221, off sc0
	v_readlane_b32 s4, v254, 1
	s_add_i32 s8, s4, 5
	v_mul_lo_u32 v1, s8, v213
	s_waitcnt vmcnt(0)
	v_add_u32_e32 v0, 1, v0
	v_cmp_eq_u32_e32 vcc, v0, v1
	s_and_saveexec_b64 s[4:5], vcc
	s_cbranch_execz .LBB0_782
	s_mov_b64 s[6:7], exec
	v_mbcnt_lo_u32_b32 v0, s6, 0
	v_mbcnt_hi_u32_b32 v0, s7, v0
	v_cmp_eq_u32_e32 vcc, 0, v0
	s_and_b64 s[10:11], exec, vcc
	s_mov_b64 exec, s[10:11]
	s_cbranch_execz .LBB0_782
	s_bcnt1_i32_b64 s6, s[6:7]
	v_mov_b32_e32 v0, s6
	v_readlane_b32 s6, v253, 10
	v_readlane_b32 s7, v253, 11
	s_nop 4
	global_atomic_add v179, v0, s[6:7]

; DI int otid() { int t = threadIdx.x; asm volatile("" : "+v"(t)); return t; }
; template <class PF, class EF>
; DI void gemm_stream(int lda, int ldw, int K, unsigned char* smem, PF ptrs, EF epi) {
;   const int tid = otid(), lane = tid & 63, w = tid >> 6;
;   const int wm = w >> 2, wn = w & 3, r = lane & 31, h = lane >> 5;
;   unsigned char* sbase = smem + GS_BASE;
;   constexpr int SLOT = 512 * 64;
;   const int nh = K >> 5;
;   const int c0 = (h ^ ((r >> 2) & 3)) * 16, c1 = c0 ^ 32;
;   const int aoff = (wm * 128 + r) * 64, boff = (256 + wn * 64 + r) * 64;
;   const int lr16 = lane >> 2, lchunk = (lane & 3) ^ ((lane >> 4) & 3);
;   const int wu = __builtin_amdgcn_readfirstlane(w);
;   const bool isB = wu >= 4;
;   const unsigned goff = isB ? (unsigned)((((wu - 4) * 64 + 2 * lr16) * ldw + lchunk * 8) * 2)
;                             : (unsigned)(((wu * 64 + lr16) * lda + lchunk * 8) * 2);
; DI void gbar(unsigned* ctl, unsigned& k) {
;     ...
;     while (__hip_atomic_load(gl, __ATOMIC_RELAXED, __HIP_MEMORY_SCOPE_AGENT) < k * ngroups) __builtin_amdgcn_s_sleep(1);
;     __threadfence();
;   }
;   __syncthreads();
.LBB0_784:
	s_sleep 1
	global_load_dword v1, v179, s[6:7] sc1
	s_waitcnt vmcnt(0)
	v_cmp_ge_u32_e32 vcc, v1, v0
	s_or_b64 s[4:5], vcc, s[4:5]
	s_andn2_b64 exec, exec, s[4:5]
	s_cbranch_execnz .LBB0_784
.LBB0_785:
	buffer_inv sc1
.LBB0_786:
	s_or_b64 exec, exec, s[2:3]
	v_mov_b32_e32 v0, v212
	v_mov_b32_e32 v1, v212
	s_barrier
	s_mov_b64 s[4:5], -1
	v_readfirstlane_b32 s7, v1
	v_lshrrev_b32_e32 v2, 4, v1
	s_ashr_i32 s6, s7, 6
	v_bitop3_b32 v2, v2, 3, v1 bitop3:0x48
	s_cmp_gt_i32 s6, 3
	v_bfe_u32 v0, v1, 2, 4
	s_cselect_b64 s[2:3], -1, 0
	s_cmp_lt_i32 s6, 4
	v_lshlrev_b32_e32 v2, 4, v2
	s_cbranch_scc0 .LBB0_788
	s_and_b32 s4, s7, 0x1fffc0
	v_or_b32_e32 v3, s4, v0
	v_lshl_or_b32 v182, v3, 11, v2
	s_mov_b64 s[4:5], 0

; DI int otid() { int t = threadIdx.x; asm volatile("" : "+v"(t)); return t; }
; DI void gbar(unsigned* ctl, unsigned& k) {
;   __syncthreads();
;   ++k;
;   if (otid() == 0) {
;     __threadfence();
;     const unsigned x = blockIdx.x & 7;
;     const unsigned gsz = (gridDim.x + 7 - x) >> 3;
;     const unsigned ngroups = gridDim.x < 8 ? gridDim.x : 8;
;     unsigned* gc = ctl + 64 + x * 32;
;     unsigned* gl = ctl + 32;
;     const unsigned old = __hip_atomic_fetch_add(gc, 1u, __ATOMIC_RELAXED, __HIP_MEMORY_SCOPE_AGENT);
;     if (old + 1 == k * gsz) {
;       __threadfence();
;       __hip_atomic_fetch_add(gl, 1u, __ATOMIC_RELAXED, __HIP_MEMORY_SCOPE_AGENT);
;     }
.LBB0_826:
	s_or_b64 exec, exec, s[24:25]
	v_mov_b32_e32 v0, v212
	s_barrier
	s_nop 0
	v_cmp_eq_u32_e32 vcc, 0, v0
	s_and_saveexec_b64 s[2:3], vcc
	s_movk_i32 s9, 0x1600
	s_cbranch_execz .LBB0_834
	buffer_wbl2 sc1
	s_waitcnt vmcnt(0)
	buffer_inv sc1
	global_atomic_add v0, v[176:177], v221, off sc0
	v_readlane_b32 s4, v254, 1
	s_add_i32 s8, s4, 6
	v_mul_lo_u32 v1, s8, v213
	s_waitcnt vmcnt(0)
	v_add_u32_e32 v0, 1, v0
	v_cmp_eq_u32_e32 vcc, v0, v1
	s_and_saveexec_b64 s[4:5], vcc
	s_cbranch_execz .LBB0_830
	s_mov_b64 s[6:7], exec
	v_mbcnt_lo_u32_b32 v0, s6, 0
	v_mbcnt_hi_u32_b32 v0, s7, v0
	v_cmp_eq_u32_e32 vcc, 0, v0
	s_and_b64 s[10:11], exec, vcc
	s_mov_b64 exec, s[10:11]
	s_cbranch_execz .LBB0_830
	s_bcnt1_i32_b64 s6, s[6:7]
	v_mov_b32_e32 v0, s6
	v_readlane_b32 s6, v253, 10
	v_readlane_b32 s7, v253, 11
	s_nop 4
	global_atomic_add v179, v0, s[6:7]

; DI int otid() { int t = threadIdx.x; asm volatile("" : "+v"(t)); return t; }
; template <class PF, class EF>
; DI void gemm_stream(int lda, int ldw, int K, unsigned char* smem, PF ptrs, EF epi) {
;   const int tid = otid(), lane = tid & 63, w = tid >> 6;
;   const int wm = w >> 2, wn = w & 3, r = lane & 31, h = lane >> 5;
;   unsigned char* sbase = smem + GS_BASE;
;   constexpr int SLOT = 512 * 64;
;   const int nh = K >> 5;
;   const int c0 = (h ^ ((r >> 2) & 3)) * 16, c1 = c0 ^ 32;
;   const int aoff = (wm * 128 + r) * 64, boff = (256 + wn * 64 + r) * 64;
;   const int lr16 = lane >> 2, lchunk = (lane & 3) ^ ((lane >> 4) & 3);
;   const int wu = __builtin_amdgcn_readfirstlane(w);
;   const bool isB = wu >= 4;
;   const unsigned goff = isB ? (unsigned)((((wu - 4) * 64 + 2 * lr16) * ldw + lchunk * 8) * 2)
;                             : (unsigned)(((wu * 64 + lr16) * lda + lchunk * 8) * 2);
; DI void gbar(unsigned* ctl, unsigned& k) {
;     ...
;     while (__hip_atomic_load(gl, __ATOMIC_RELAXED, __HIP_MEMORY_SCOPE_AGENT) < k * ngroups) __builtin_amdgcn_s_sleep(1);
;     __threadfence();
;   }
;   __syncthreads();
.LBB0_832:
	s_sleep 1
	global_load_dword v1, v179, s[6:7] sc1
	s_waitcnt vmcnt(0)
	v_cmp_ge_u32_e32 vcc, v1, v0
	s_or_b64 s[4:5], vcc, s[4:5]
	s_andn2_b64 exec, exec, s[4:5]
	s_cbranch_execnz .LBB0_832
.LBB0_833:
	buffer_inv sc1
.LBB0_834:
	s_or_b64 exec, exec, s[2:3]
	v_mov_b32_e32 v0, v212
	s_barrier
	s_nop 0
	v_mov_b32_e32 v0, v212
	s_nop 0
	v_readfirstlane_b32 s4, v0
	s_ashr_i32 s6, s4, 6
	s_cmp_gt_i32 s6, 3
	v_lshrrev_b32_e32 v2, 4, v0
	s_cselect_b64 s[2:3], -1, 0
	s_and_b32 s7, s4, 0x7fffffc0
	v_bfe_u32 v1, v0, 2, 4
	v_bitop3_b32 v2, v2, 3, v0 bitop3:0x48
	s_cmp_lt_i32 s6, 4
	s_mov_b64 s[4:5], -1
	s_cbranch_scc0 .LBB0_836
	v_or_b32_e32 v3, s7, v1
	v_mul_lo_u32 v3, v3, s9
	v_lshl_or_b32 v178, v2, 4, v3
	s_mov_b64 s[4:5], 0

; DI int otid() { int t = threadIdx.x; asm volatile("" : "+v"(t)); return t; }
; DI void gbar(unsigned* ctl, unsigned& k) {
;   __syncthreads();
;   ++k;
;   if (otid() == 0) {
;     __threadfence();
;     const unsigned x = blockIdx.x & 7;
;     const unsigned gsz = (gridDim.x + 7 - x) >> 3;
;     const unsigned ngroups = gridDim.x < 8 ? gridDim.x : 8;
;     unsigned* gc = ctl + 64 + x * 32;
;     unsigned* gl = ctl + 32;
;     const unsigned old = __hip_atomic_fetch_add(gc, 1u, __ATOMIC_RELAXED, __HIP_MEMORY_SCOPE_AGENT);
;     if (old + 1 == k * gsz) {
;       __threadfence();
;       __hip_atomic_fetch_add(gl, 1u, __ATOMIC_RELAXED, __HIP_MEMORY_SCOPE_AGENT);
;     }
.LBB0_884:
	v_readlane_b32 s0, v254, 1
	v_mov_b32_e32 v0, v212
	s_barrier
	s_barrier
	s_add_i32 s28, s0, 7
	s_nop 0
	v_cmp_eq_u32_e32 vcc, 0, v0
	s_and_saveexec_b64 s[0:1], vcc
	s_cbranch_execz .LBB0_892
	buffer_wbl2 sc1
	s_waitcnt vmcnt(0)
	buffer_inv sc1
	global_atomic_add v0, v[176:177], v221, off sc0
	v_mul_lo_u32 v1, s28, v213
	s_waitcnt vmcnt(0)
	v_add_u32_e32 v0, 1, v0
	v_cmp_eq_u32_e32 vcc, v0, v1
	s_and_saveexec_b64 s[2:3], vcc
	s_cbranch_execz .LBB0_888
	s_mov_b64 s[4:5], exec
	v_mbcnt_lo_u32_b32 v0, s4, 0
	v_mbcnt_hi_u32_b32 v0, s5, v0
	v_cmp_eq_u32_e32 vcc, 0, v0
	s_and_b64 s[6:7], exec, vcc
	s_mov_b64 exec, s[6:7]
	s_cbranch_execz .LBB0_888
	s_bcnt1_i32_b64 s4, s[4:5]
	v_mov_b32_e32 v0, s4
	v_readlane_b32 s4, v253, 10
	v_readlane_b32 s5, v253, 11
	s_nop 4
	global_atomic_add v179, v0, s[4:5]

; DI void ln_pass(const Params& p, int mode, int l, unsigned char* smem) {
;     ...
;   if (gates) {
;     const float* wi = p.in[12] + (size_t)lm * 1024 * 3592 + 3072;
;     for (int idx = tid; idx < 8192; idx += NTHR) {
;       const int c = idx >> 3, j = idx & 7;
;       wl[j * 1024 + c] = wi[(size_t)c * 3592 + j];
;     }
; #pragma unroll
;     for (int j = 0; j < 8; ++j) bif[j] = p.in[13][lm * 8 + j];
;   }
; DI void gbar(unsigned* ctl, unsigned& k) {
;     ...
;     while (__hip_atomic_load(gl, __ATOMIC_RELAXED, __HIP_MEMORY_SCOPE_AGENT) < k * ngroups) __builtin_amdgcn_s_sleep(1);
;     __threadfence();
;   }
;   __syncthreads();
.LBB0_890:
	s_sleep 1
	global_load_dword v1, v179, s[4:5] sc1
	s_waitcnt vmcnt(0)
	v_cmp_ge_u32_e32 vcc, v1, v0
	s_or_b64 s[2:3], vcc, s[2:3]
	s_andn2_b64 exec, exec, s[2:3]
	s_cbranch_execnz .LBB0_890
.LBB0_891:
	buffer_inv sc1
.LBB0_892:
	s_or_b64 exec, exec, s[0:1]
	v_readlane_b32 s2, v254, 12
	v_readlane_b32 s3, v254, 13
	s_andn2_b64 vcc, exec, s[2:3]
	v_mov_b32_e32 v88, v212
	v_cndmask_b32_e64 v0, 0, 1, s[2:3]
	v_readlane_b32 s2, v254, 14
	v_cmp_ne_u32_e64 s[0:1], 1, v0
	s_add_i32 s10, s2, 1
	s_barrier
	v_readlane_b32 s3, v254, 15
	s_cbranch_vccnz .LBB0_906
	s_movk_i32 s2, 0x2000
	v_cmp_gt_i32_e32 vcc, s2, v88
	s_and_saveexec_b64 s[2:3], vcc
	s_cbranch_execz .LBB0_905
	v_readlane_b32 s36, v252, 16
	s_mul_i32 s4, s10, 0xe08000
	v_readlane_b32 s44, v252, 24
	v_readlane_b32 s45, v252, 25
	s_add_u32 s4, s44, s4
	v_and_b32_e32 v2, 7, v88
	s_addc_u32 s5, s45, 0
	v_lshlrev_b32_e32 v178, 2, v2
	s_waitcnt vmcnt(6)
	v_lshl_add_u32 v4, v2, 12, 0
	v_max_i32_e32 v2, 0x1e00, v88
	v_lshl_add_u64 v[0:1], s[4:5], 0, v[178:179]
	s_mov_b64 s[4:5], 0x3000
	v_sub_u32_e32 v2, v2, v88
	v_lshl_add_u64 v[0:1], v[0:1], 0, s[4:5]
	v_add_u32_e32 v3, 0x1ff, v2
	s_movk_i32 s4, 0x1ff
	v_cmp_lt_u32_e32 vcc, s4, v3
	s_mov_b64 s[6:7], -1
	v_mov_b32_e32 v2, v88
	v_readlane_b32 s37, v252, 17
	v_readlane_b32 s38, v252, 18
	v_readlane_b32 s39, v252, 19
	v_readlane_b32 s40, v252, 20
	v_readlane_b32 s41, v252, 21
	v_readlane_b32 s42, v252, 22
	v_readlane_b32 s43, v252, 23
	v_readlane_b32 s46, v252, 26
	v_readlane_b32 s47, v252, 27
	v_readlane_b32 s48, v252, 28
	v_readlane_b32 s49, v252, 29
	v_readlane_b32 s50, v252, 30
	v_readlane_b32 s51, v252, 31
	s_and_saveexec_b64 s[4:5], vcc
	s_cbranch_execz .LBB0_902
	v_lshrrev_b32_e32 v5, 9, v3
	v_add_u32_e32 v89, 0x200, v88
	v_add_u32_e32 v6, -1, v5
	v_cmp_lt_u32_e32 vcc, 1, v6
	v_mov_b64_e32 v[2:3], v[88:89]
	s_and_saveexec_b64 s[6:7], vcc
	s_cbranch_execz .LBB0_899
	v_lshrrev_b32_e32 v2, 1, v6
	v_add_u32_e32 v2, 1, v2
	v_and_b32_e32 v7, -2, v2
	s_mov_b64 s[8:9], 0
	v_mov_b64_e32 v[2:3], v[88:89]
	s_movk_i32 s11, 0x3820

; DI int otid() { int t = threadIdx.x; asm volatile("" : "+v"(t)); return t; }
; DI void gbar(unsigned* ctl, unsigned& k) {
;   __syncthreads();
;   ++k;
;   if (otid() == 0) {
;     __threadfence();
;     const unsigned x = blockIdx.x & 7;
;     const unsigned gsz = (gridDim.x + 7 - x) >> 3;
;     const unsigned ngroups = gridDim.x < 8 ? gridDim.x : 8;
;     unsigned* gc = ctl + 64 + x * 32;
;     unsigned* gl = ctl + 32;
;     const unsigned old = __hip_atomic_fetch_add(gc, 1u, __ATOMIC_RELAXED, __HIP_MEMORY_SCOPE_AGENT);
;     if (old + 1 == k * gsz) {
;       __threadfence();
;       __hip_atomic_fetch_add(gl, 1u, __ATOMIC_RELAXED, __HIP_MEMORY_SCOPE_AGENT);
;     }
; __global__ void __launch_bounds__(NTHR) fwd_megakernel(Params p) {
;     ...
;     if (PH & 512) ln_pass(p, 2, l, smem);
;     if (l == 0) gbar(bar, epoch);
.LBB0_951:
	s_or_b64 exec, exec, s[8:9]
	s_and_b64 vcc, exec, s[0:1]
	s_cbranch_vccnz .LBB0_207
	v_readlane_b32 s0, v254, 1
	s_waitcnt vmcnt(9)
	v_mov_b32_e32 v0, v212
	s_barrier
	s_add_i32 s28, s0, 8
	s_nop 0
	v_cmp_eq_u32_e32 vcc, 0, v0
	s_and_saveexec_b64 s[0:1], vcc
	s_cbranch_execz .LBB0_206
	buffer_wbl2 sc1
	s_waitcnt vmcnt(0)
	buffer_inv sc1
	global_atomic_add v0, v[176:177], v221, off sc0
	v_mul_lo_u32 v1, s28, v213
	s_waitcnt vmcnt(0)
	v_add_u32_e32 v0, 1, v0
	v_cmp_eq_u32_e32 vcc, v0, v1
	s_and_saveexec_b64 s[2:3], vcc
	s_cbranch_execz .LBB0_956
	s_mov_b64 s[4:5], exec
	v_mbcnt_lo_u32_b32 v0, s4, 0
	v_mbcnt_hi_u32_b32 v0, s5, v0
	v_cmp_eq_u32_e32 vcc, 0, v0
	s_and_b64 s[6:7], exec, vcc
	s_mov_b64 exec, s[6:7]
	s_cbranch_execz .LBB0_956
	s_bcnt1_i32_b64 s4, s[4:5]
	v_mov_b32_e32 v0, s4
	v_readlane_b32 s4, v253, 10
	v_readlane_b32 s5, v253, 11
	s_nop 4
	global_atomic_add v179, v0, s[4:5]
